# phase C sel/window chunks: validity mask applied via QK MFMA C input (0/-inf tile) instead of 8 cndmask per head; score fmas as v_pk_fma_f32
# speedup vs baseline: 1.0088x; 1.0088x over previous
; #define MFMA16(a, b, c) __builtin_amdgcn_mfma_f32_16x16x32_bf16((a), (b), (c), 0, 0, 0)
; DI unsigned pk2(float lo, float hi) { f32x2 v = {lo, hi}; bf16x2_t b = __builtin_convertvector(v, bf16x2_t); return __builtin_bit_cast(unsigned, b); }
; template <int MODE>
; DI void nsa_chunk(const KVFrag& f, int kb, int t, bool selbit, const bf16x8 (&qf)[4][2], f32x4 (&O)[4][4], float (&m)[4], float (&l)[4], int quad, bool online) {
;     ...
;     float pv[8]; float ps = 0.f;
; #pragma unroll
;     for (int idx = 0; idx < 8; ++idx) { pv[idx] = val[idx] ? __builtin_amdgcn_exp2f(fmaf(s[idx >> 2][idx & 3], SC, -mn)) : 0.f; ps += pv[idx]; }
;     l[hh] += ps;
;     const bf16x8 pf = mk8((u32x4){pk2(pv[0], pv[1]), pk2(pv[2], pv[3]), pk2(pv[4], pv[5]), pk2(pv[6], pv[7])});
; #pragma unroll
;     for (int dt = 0; dt < 4; ++dt) O[hh][dt] = MFMA16(f.v[dt], pf, O[hh][dt]);
.LBB0_725:
	v_add_f32_e32 v140, 0, v152
	v_add_f32_e32 v140, v153, v140
	v_add_f32_e32 v140, v154, v140
	v_add_f32_e32 v140, v155, v140
	v_add_f32_e32 v140, v148, v140
	v_add_f32_e32 v140, v149, v140
	v_add_f32_e32 v140, v150, v140
	v_add_f32_e32 v140, v151, v140
	v_add_f32_e32 v165, v165, v140
	v_add_f32_e32 v140, 0, v189
	v_add_f32_e32 v140, v190, v140
	v_add_f32_e32 v140, v191, v140
	v_add_f32_e32 v140, v192, v140
	v_add_f32_e32 v140, v193, v140
	v_add_f32_e32 v140, v194, v140
	v_add_f32_e32 v140, v195, v140
	v_add_f32_e32 v140, v196, v140
	v_add_f32_e32 v166, v166, v140
	v_add_f32_e32 v140, 0, v181
	v_add_f32_e32 v140, v182, v140
	v_add_f32_e32 v140, v183, v140
	v_add_f32_e32 v140, v184, v140
	v_pk_fma_f32 v[136:137], v[136:137], s[34:35], v[180:181] op_sel_hi:[1,0,0] neg_lo:[0,0,1] neg_hi:[0,0,1]
	v_pk_fma_f32 v[138:139], v[138:139], s[34:35], v[180:181] op_sel_hi:[1,0,0] neg_lo:[0,0,1] neg_hi:[0,0,1]
	v_pk_fma_f32 v[132:133], v[132:133], s[34:35], v[180:181] op_sel_hi:[1,0,0] neg_lo:[0,0,1] neg_hi:[0,0,1]
	v_pk_fma_f32 v[134:135], v[134:135], s[34:35], v[180:181] op_sel_hi:[1,0,0] neg_lo:[0,0,1] neg_hi:[0,0,1]
	v_add_f32_e32 v140, v185, v140
	v_add_f32_e32 v140, v186, v140
	v_add_f32_e32 v140, v187, v140
	v_add_f32_e32 v140, v188, v140
	v_add_f32_e32 v167, v167, v140
	v_exp_f32_e32 v136, v136
	v_exp_f32_e32 v137, v137
	v_exp_f32_e32 v138, v138
	v_exp_f32_e32 v139, v139
	v_exp_f32_e32 v140, v132
	v_exp_f32_e32 v141, v133
	v_exp_f32_e32 v142, v134
	v_exp_f32_e32 v143, v135
	v_cvt_pk_bf16_f32 v132, v136, v137
	v_cvt_pk_bf16_f32 v133, v138, v139
	v_cvt_pk_bf16_f32 v134, v140, v141
	v_cvt_pk_bf16_f32 v135, v142, v143
	s_nop 1
	v_mfma_f32_16x16x32_bf16 v[56:59], v[128:131], v[132:135], v[56:59]
	v_add_f32_e32 v128, 0, v136
	v_add_f32_e32 v128, v137, v128
	v_add_f32_e32 v128, v138, v128
	v_mfma_f32_16x16x32_bf16 v[52:55], v[124:127], v[132:135], v[52:55]
	v_add_f32_e32 v124, v139, v128
	v_add_f32_e32 v124, v140, v124
	v_add_f32_e32 v124, v141, v124
	v_mfma_f32_16x16x32_bf16 v[48:51], v[120:123], v[132:135], v[48:51]
	v_add_f32_e32 v120, v142, v124
	v_add_f32_e32 v120, v143, v120
	v_add_f32_e32 v164, v164, v120
	v_mfma_f32_16x16x32_bf16 v[44:47], v[116:119], v[132:135], v[44:47]

; #define MFMA16(a, b, c) __builtin_amdgcn_mfma_f32_16x16x32_bf16((a), (b), (c), 0, 0, 0)
; template <int MODE>
; DI void nsa_chunk(const KVFrag& f, int kb, int t, bool selbit, const bf16x8 (&qf)[4][2], f32x4 (&O)[4][4], float (&m)[4], float (&l)[4], int quad, bool online) {
;   const float SC = 0.125f * 1.44269504089f;
;   bool val[8];
; #pragma unroll
;   for (int idx = 0; idx < 8; ++idx) {
;     const int key = kb + 8 * quad + idx;
;     val[idx] = MODE == 0 ? (selbit && key <= t) : (key <= t && key > t - 512);
;   }
; #pragma unroll
;   for (int hh = 0; hh < 4; ++hh) {
;     f32x4 s[2];
; #pragma unroll
;     for (int a = 0; a < 2; ++a) { s[a] = MFMA16(f.k[a][0], qf[hh][0], ((f32x4){0.f, 0.f, 0.f, 0.f})); s[a] = MFMA16(f.k[a][1], qf[hh][1], s[a]); }
;     float mn = m[hh];
;     if (online) {
;       float cm = -1e30f;
; #pragma unroll
;       for (int idx = 0; idx < 8; ++idx) if (val[idx]) cm = fmaxf(cm, s[idx >> 2][idx & 3] * SC);
;       cm = fmaxf(cm, __shfl_xor(cm, 16)); cm = fmaxf(cm, __shfl_xor(cm, 32));
;       mn = fmaxf(mn, cm);
;       const float alpha = __builtin_amdgcn_exp2f(m[hh] - mn);
;       m[hh] = mn; l[hh] *= alpha;
; #pragma unroll
;       for (int dt = 0; dt < 4; ++dt) O[hh][dt] = O[hh][dt] * alpha;
;     }
; template <int MODE>
; DI void nsa_branch(const bf16_t* __restrict__ Kb, const bf16_t* __restrict__ Vtb, unsigned char* lds, int nb, int t, int cur, unsigned selmask, unsigned umall,
;                    const bf16x8 (&qf)[4][2], f32x4 (&O)[4][4], float (&m)[4], float (&l)[4], bool online) {
;     ...
;   for (int n = 0; n < N; n += 2) {
;     const int j = blist[n >> 1];
;     const bool won = MODE == 0 ? ((umall >> j) & 1u) != 0 : (j >= cur - 8 && j <= cur);
;     const bool bit = (selmask >> j) & 1u;
;     ra = *(const u32x4*)(gsrc + (long)kbof(min(n + 2, N - 2)) * gmul);
;     if (won) { KVFrag f; nsa_ldsfrag(f, slot0, qi, quad); nsa_chunk<MODE>(f, j * 64, t, bit, qf, O, m, l, quad, online); }
.LBB0_727:
	s_sub_u32 s58, s56, 0x14c20
	s_lshr_b32 s58, s58, 2
	v_readlane_b32 s0, v216, s58
	s_nop 1
	v_mov_b32_e32 v181, s0
	s_lshl_b32 s10, 1, s0
	s_and_b32 s11, s10, s42
	s_cmp_lg_u32 s11, 0
	s_cselect_b64 s[0:1], -1, 0
	s_add_i32 s57, s54, -1
	s_min_i32 s12, s57, s43
	s_lshr_b32 s12, s12, 1
	v_readlane_b32 s58, v216, s12
	v_and_b32_e32 v116, s10, v171
	v_cmp_ne_u32_e64 s[12:13], 0, v116
	v_cndmask_b32_e64 v116, 0, 1, s[8:9]
	s_lshl_b32 s58, s58, 6
	s_ashr_i32 s59, s58, 31
	s_lshl_b64 s[58:59], s[58:59], 7
	s_cmp_eq_u32 s11, 0
	v_lshl_add_u64 v[112:113], v[168:169], 0, s[58:59]
	global_load_dwordx4 v[112:115], v[112:113], off
	v_cmp_ne_u32_e64 s[10:11], 1, v116
	s_cbranch_scc1 .LBB0_737
	v_lshl_or_b32 v182, v181, 6, v173
	v_cmp_le_i32_e32 vcc, v182, v160
	s_and_b64 s[16:17], s[12:13], vcc
	v_cmp_lt_i32_e32 vcc, v182, v160
	v_or_b32_e32 v148, 2, v182
	s_and_b64 s[18:19], s[12:13], vcc
	v_cmp_le_i32_e32 vcc, v148, v160
	v_or_b32_e32 v148, 3, v182
	s_and_b64 s[44:45], s[12:13], vcc
	v_cmp_le_i32_e32 vcc, v148, v160
	v_or_b32_e32 v148, 4, v182
	ds_read_b128 v[136:139], v176
	ds_read_b128 v[140:143], v176 offset:64
	ds_read_b128 v[144:147], v176 offset:576
	ds_read_b128 v[132:135], v176 offset:640
	ds_read_b128 v[128:131], v177
	ds_read_b128 v[124:127], v177 offset:1280
	ds_read_b128 v[120:123], v177 offset:2560
	ds_read_b128 v[116:119], v177 offset:3840
	s_and_b64 s[46:47], s[12:13], vcc
	v_cmp_le_i32_e32 vcc, v148, v160
	v_or_b32_e32 v152, 5, v182
	s_and_b64 s[14:15], s[12:13], vcc
	v_cmp_le_i32_e32 vcc, v152, v160
	v_or_b32_e32 v183, 6, v182
	s_and_b64 s[48:49], s[12:13], vcc
	v_cmp_le_i32_e32 vcc, v183, v160
	v_or_b32_e32 v182, 7, v182
	s_and_b64 s[50:51], s[12:13], vcc
	v_cmp_le_i32_e32 vcc, v182, v160
	s_and_b64 s[52:53], s[12:13], vcc
	s_and_b64 vcc, exec, s[10:11]
	v_mov_b32_e32 v226, 0xff800000
	v_cndmask_b32_e64 v218, v226, 0, s[16:17]
	v_cndmask_b32_e64 v219, v226, 0, s[18:19]
	v_cndmask_b32_e64 v220, v226, 0, s[44:45]
	v_cndmask_b32_e64 v221, v226, 0, s[46:47]
	v_cndmask_b32_e64 v222, v226, 0, s[14:15]
	v_cndmask_b32_e64 v223, v226, 0, s[48:49]
	v_cndmask_b32_e64 v224, v226, 0, s[50:51]
	v_cndmask_b32_e64 v225, v226, 0, s[52:53]
	s_nop 1
	s_waitcnt lgkmcnt(7)
	v_mfma_f32_16x16x32_bf16 v[148:151], v[136:139], v[8:11], v[218:221]
	s_waitcnt lgkmcnt(6)
	v_mfma_f32_16x16x32_bf16 v[152:155], v[140:143], v[12:15], v[148:151]
	s_waitcnt lgkmcnt(5)
	v_mfma_f32_16x16x32_bf16 v[148:151], v[144:147], v[8:11], v[222:225]
	s_waitcnt lgkmcnt(4)
	v_mfma_f32_16x16x32_bf16 v[148:151], v[132:135], v[12:15], v[148:151]
	s_nop 7
	s_cbranch_vccnz .LBB0_730
	v_mul_f32_e32 v182, 0x3e38aa3b, v152
	v_max_f32_e32 v182, 0xf149f2ca, v182
	v_cndmask_b32_e64 v182, v232, v182, s[16:17]
	v_mul_f32_e32 v183, 0x3e38aa3b, v153
	v_max_f32_e32 v183, v182, v183
	v_cndmask_b32_e64 v182, v182, v183, s[18:19]
	v_mul_f32_e32 v183, 0x3e38aa3b, v154
	v_max_f32_e32 v183, v182, v183
	v_cndmask_b32_e64 v182, v182, v183, s[44:45]
	v_mul_f32_e32 v183, 0x3e38aa3b, v155
	v_max_f32_e32 v183, v182, v183
	v_cndmask_b32_e64 v182, v182, v183, s[46:47]
	v_mul_f32_e32 v183, 0x3e38aa3b, v148
	v_max_f32_e32 v183, v182, v183
	v_cndmask_b32_e64 v182, v182, v183, s[14:15]
	v_mul_f32_e32 v183, 0x3e38aa3b, v149
	v_max_f32_e32 v184, v182, v182
	v_max_f32_e32 v183, v184, v183
	v_cndmask_b32_e64 v182, v182, v183, s[48:49]
	v_mul_f32_e32 v183, 0x3e38aa3b, v150
	v_max_f32_e32 v184, v182, v182
	v_max_f32_e32 v183, v184, v183
	v_cndmask_b32_e64 v182, v182, v183, s[50:51]
	v_mul_f32_e32 v183, 0x3e38aa3b, v151
	v_max_f32_e32 v184, v182, v182
	v_max_f32_e32 v183, v184, v183
	v_cndmask_b32_e64 v182, v182, v183, s[52:53]
	ds_bpermute_b32 v183, v175, v182
	v_max_f32_e32 v182, v182, v182
	s_waitcnt lgkmcnt(0)
	v_max_f32_e32 v183, v183, v183
	v_max_f32_e32 v182, v182, v183
	ds_bpermute_b32 v183, v159, v182
	s_waitcnt lgkmcnt(0)
	v_max3_f32 v183, v3, v182, v183
	v_sub_f32_e32 v3, v3, v183
	v_exp_f32_e32 v182, v3
	v_mov_b32_e32 v3, v183
	v_mul_f32_e32 v167, v167, v182
	v_pk_mul_f32 v[106:107], v[106:107], v[182:183] op_sel_hi:[1,0]
	v_pk_mul_f32 v[104:105], v[104:105], v[182:183] op_sel_hi:[1,0]
	v_pk_mul_f32 v[102:103], v[102:103], v[182:183] op_sel_hi:[1,0]
	v_pk_mul_f32 v[100:101], v[100:101], v[182:183] op_sel_hi:[1,0]
	v_pk_mul_f32 v[98:99], v[98:99], v[182:183] op_sel_hi:[1,0]
	v_pk_mul_f32 v[96:97], v[96:97], v[182:183] op_sel_hi:[1,0]
	v_pk_mul_f32 v[94:95], v[94:95], v[182:183] op_sel_hi:[1,0]
	v_pk_mul_f32 v[92:93], v[92:93], v[182:183] op_sel_hi:[1,0]
; #define MFMA16(a, b, c) __builtin_amdgcn_mfma_f32_16x16x32_bf16((a), (b), (c), 0, 0, 0)
; DI unsigned pk2(float lo, float hi) { f32x2 v = {lo, hi}; bf16x2_t b = __builtin_convertvector(v, bf16x2_t); return __builtin_bit_cast(unsigned, b); }
; template <int MODE>
; DI void nsa_chunk(const KVFrag& f, int kb, int t, bool selbit, const bf16x8 (&qf)[4][2], f32x4 (&O)[4][4], float (&m)[4], float (&l)[4], int quad, bool online) {
;     ...
;   for (int hh = 0; hh < 4; ++hh) {
;     f32x4 s[2];
; #pragma unroll
;     for (int a = 0; a < 2; ++a) { s[a] = MFMA16(f.k[a][0], qf[hh][0], ((f32x4){0.f, 0.f, 0.f, 0.f})); s[a] = MFMA16(f.k[a][1], qf[hh][1], s[a]); }
;     float mn = m[hh];
;     if (online) {
;       float cm = -1e30f;
; #pragma unroll
;       for (int idx = 0; idx < 8; ++idx) if (val[idx]) cm = fmaxf(cm, s[idx >> 2][idx & 3] * SC);
;       cm = fmaxf(cm, __shfl_xor(cm, 16)); cm = fmaxf(cm, __shfl_xor(cm, 32));
;       mn = fmaxf(mn, cm);
;       const float alpha = __builtin_amdgcn_exp2f(m[hh] - mn);
;       m[hh] = mn; l[hh] *= alpha;
; #pragma unroll
;       for (int dt = 0; dt < 4; ++dt) O[hh][dt] = O[hh][dt] * alpha;
;     }
;     float pv[8]; float ps = 0.f;
; #pragma unroll
;     for (int idx = 0; idx < 8; ++idx) { pv[idx] = val[idx] ? __builtin_amdgcn_exp2f(fmaf(s[idx >> 2][idx & 3], SC, -mn)) : 0.f; ps += pv[idx]; }
;     l[hh] += ps;
;     const bf16x8 pf = mk8((u32x4){pk2(pv[0], pv[1]), pk2(pv[2], pv[3]), pk2(pv[4], pv[5]), pk2(pv[6], pv[7])});
; #pragma unroll
;     for (int dt = 0; dt < 4; ++dt) O[hh][dt] = MFMA16(f.v[dt], pf, O[hh][dt]);
.LBB0_730:
	v_pk_fma_f32 v[152:153], v[152:153], s[34:35], v[2:3] op_sel:[0,0,1] op_sel_hi:[1,0,1] neg_lo:[0,0,1] neg_hi:[0,0,1]
	v_pk_fma_f32 v[154:155], v[154:155], s[34:35], v[2:3] op_sel:[0,0,1] op_sel_hi:[1,0,1] neg_lo:[0,0,1] neg_hi:[0,0,1]
	s_nop 0
	v_pk_fma_f32 v[148:149], v[148:149], s[34:35], v[2:3] op_sel:[0,0,1] op_sel_hi:[1,0,1] neg_lo:[0,0,1] neg_hi:[0,0,1]
	v_pk_fma_f32 v[150:151], v[150:151], s[34:35], v[2:3] op_sel:[0,0,1] op_sel_hi:[1,0,1] neg_lo:[0,0,1] neg_hi:[0,0,1]
	v_exp_f32_e32 v182, v152
	v_exp_f32_e32 v183, v153
	v_exp_f32_e32 v184, v154
	v_exp_f32_e32 v185, v155
	v_exp_f32_e32 v186, v148
	v_exp_f32_e32 v187, v149
	v_exp_f32_e32 v188, v150
	v_exp_f32_e32 v189, v151
	v_cvt_pk_bf16_f32 v148, v182, v183
	v_cvt_pk_bf16_f32 v149, v184, v185
	v_cvt_pk_bf16_f32 v150, v186, v187
	v_cvt_pk_bf16_f32 v151, v188, v189
	s_and_b64 vcc, exec, s[10:11]
	s_waitcnt lgkmcnt(3)
	v_mfma_f32_16x16x32_bf16 v[104:107], v[128:131], v[148:151], v[104:107]
	s_waitcnt lgkmcnt(2)
	v_mfma_f32_16x16x32_bf16 v[100:103], v[124:127], v[148:151], v[100:103]
	s_waitcnt lgkmcnt(1)
	v_mfma_f32_16x16x32_bf16 v[96:99], v[120:123], v[148:151], v[96:99]
	s_waitcnt lgkmcnt(0)
	v_mfma_f32_16x16x32_bf16 v[92:95], v[116:119], v[148:151], v[92:95]
	v_mfma_f32_16x16x32_bf16 v[148:151], v[136:139], v[16:19], v[218:221]
	v_mfma_f32_16x16x32_bf16 v[152:155], v[140:143], v[20:23], v[148:151]
	v_mfma_f32_16x16x32_bf16 v[148:151], v[144:147], v[16:19], v[222:225]
	v_mfma_f32_16x16x32_bf16 v[148:151], v[132:135], v[20:23], v[148:151]
	s_cbranch_vccnz .LBB0_732
	s_nop 4
	v_mul_f32_e32 v190, 0x3e38aa3b, v152
	v_max_f32_e32 v190, 0xf149f2ca, v190
	v_cndmask_b32_e64 v190, v232, v190, s[16:17]
	v_mul_f32_e32 v191, 0x3e38aa3b, v153
	v_max_f32_e32 v191, v190, v191
	v_cndmask_b32_e64 v190, v190, v191, s[18:19]
	v_mul_f32_e32 v191, 0x3e38aa3b, v154
	v_max_f32_e32 v191, v190, v191
	v_cndmask_b32_e64 v190, v190, v191, s[44:45]
	v_mul_f32_e32 v191, 0x3e38aa3b, v155
	v_max_f32_e32 v191, v190, v191
	v_cndmask_b32_e64 v190, v190, v191, s[46:47]
	v_mul_f32_e32 v191, 0x3e38aa3b, v148
	v_max_f32_e32 v191, v190, v191
	v_cndmask_b32_e64 v190, v190, v191, s[14:15]
	v_mul_f32_e32 v191, 0x3e38aa3b, v149
	v_max_f32_e32 v192, v190, v190
	v_max_f32_e32 v191, v192, v191
	v_cndmask_b32_e64 v190, v190, v191, s[48:49]
	v_mul_f32_e32 v191, 0x3e38aa3b, v150
	v_max_f32_e32 v192, v190, v190
	v_max_f32_e32 v191, v192, v191
	v_cndmask_b32_e64 v190, v190, v191, s[50:51]
	v_mul_f32_e32 v191, 0x3e38aa3b, v151
	v_max_f32_e32 v192, v190, v190
	v_max_f32_e32 v191, v192, v191
	v_cndmask_b32_e64 v190, v190, v191, s[52:53]
	ds_bpermute_b32 v191, v175, v190
	v_max_f32_e32 v190, v190, v190
	s_waitcnt lgkmcnt(0)
	v_max_f32_e32 v191, v191, v191
	v_max_f32_e32 v190, v190, v191
	ds_bpermute_b32 v191, v159, v190
	s_waitcnt lgkmcnt(0)
	v_max3_f32 v190, v2, v190, v191
	v_sub_f32_e32 v2, v2, v190
	v_exp_f32_e32 v2, v2
	s_nop 0
	v_mul_f32_e32 v166, v166, v2
	v_pk_mul_f32 v[90:91], v[90:91], v[2:3] op_sel_hi:[1,0]
	v_pk_mul_f32 v[88:89], v[88:89], v[2:3] op_sel_hi:[1,0]
	v_pk_mul_f32 v[86:87], v[86:87], v[2:3] op_sel_hi:[1,0]
	v_pk_mul_f32 v[84:85], v[84:85], v[2:3] op_sel_hi:[1,0]
	v_pk_mul_f32 v[82:83], v[82:83], v[2:3] op_sel_hi:[1,0]
	v_pk_mul_f32 v[80:81], v[80:81], v[2:3] op_sel_hi:[1,0]
	v_pk_mul_f32 v[78:79], v[78:79], v[2:3] op_sel_hi:[1,0]
	v_pk_mul_f32 v[76:77], v[76:77], v[2:3] op_sel_hi:[1,0]
	v_mov_b32_e32 v2, v190
.LBB0_732:
	s_nop 4
	v_pk_fma_f32 v[152:153], v[152:153], s[34:35], v[2:3] op_sel_hi:[1,0,0] neg_lo:[0,0,1] neg_hi:[0,0,1]
	v_pk_fma_f32 v[154:155], v[154:155], s[34:35], v[2:3] op_sel_hi:[1,0,0] neg_lo:[0,0,1] neg_hi:[0,0,1]
	v_pk_fma_f32 v[148:149], v[148:149], s[34:35], v[2:3] op_sel_hi:[1,0,0] neg_lo:[0,0,1] neg_hi:[0,0,1]
	v_pk_fma_f32 v[150:151], v[150:151], s[34:35], v[2:3] op_sel_hi:[1,0,0] neg_lo:[0,0,1] neg_hi:[0,0,1]
	v_exp_f32_e32 v190, v152
	v_exp_f32_e32 v191, v153
	v_exp_f32_e32 v192, v154
	v_exp_f32_e32 v193, v155
	v_exp_f32_e32 v194, v148
	v_exp_f32_e32 v195, v149
	v_exp_f32_e32 v196, v150
	v_exp_f32_e32 v197, v151
	v_cvt_pk_bf16_f32 v148, v190, v191
	v_cvt_pk_bf16_f32 v149, v192, v193
	v_cvt_pk_bf16_f32 v150, v194, v195
	v_cvt_pk_bf16_f32 v151, v196, v197
	s_and_b64 vcc, exec, s[10:11]
	s_nop 0
	v_mfma_f32_16x16x32_bf16 v[88:91], v[128:131], v[148:151], v[88:91]
	v_mfma_f32_16x16x32_bf16 v[84:87], v[124:127], v[148:151], v[84:87]
	v_mfma_f32_16x16x32_bf16 v[80:83], v[120:123], v[148:151], v[80:83]
	v_mfma_f32_16x16x32_bf16 v[76:79], v[116:119], v[148:151], v[76:79]
	v_mfma_f32_16x16x32_bf16 v[148:151], v[136:139], v[24:27], v[218:221]
	v_mfma_f32_16x16x32_bf16 v[152:155], v[140:143], v[28:31], v[148:151]
	v_mfma_f32_16x16x32_bf16 v[148:151], v[144:147], v[24:27], v[222:225]
	v_mfma_f32_16x16x32_bf16 v[148:151], v[132:135], v[28:31], v[148:151]
	s_cbranch_vccnz .LBB0_734
	s_nop 4
	v_mul_f32_e32 v198, 0x3e38aa3b, v152
	v_max_f32_e32 v198, 0xf149f2ca, v198
	v_cndmask_b32_e64 v198, v232, v198, s[16:17]
	v_mul_f32_e32 v199, 0x3e38aa3b, v153
	v_max_f32_e32 v199, v198, v199
	v_cndmask_b32_e64 v198, v198, v199, s[18:19]
	v_mul_f32_e32 v199, 0x3e38aa3b, v154
	v_max_f32_e32 v199, v198, v199
	v_cndmask_b32_e64 v198, v198, v199, s[44:45]
	v_mul_f32_e32 v199, 0x3e38aa3b, v155
	v_max_f32_e32 v199, v198, v199
	v_cndmask_b32_e64 v198, v198, v199, s[46:47]
	v_mul_f32_e32 v199, 0x3e38aa3b, v148
	v_max_f32_e32 v199, v198, v199
	v_cndmask_b32_e64 v198, v198, v199, s[14:15]
	v_mul_f32_e32 v199, 0x3e38aa3b, v149
	v_max_f32_e32 v200, v198, v198
	v_max_f32_e32 v199, v200, v199
	v_cndmask_b32_e64 v198, v198, v199, s[48:49]
	v_mul_f32_e32 v199, 0x3e38aa3b, v150
	v_max_f32_e32 v200, v198, v198
	v_max_f32_e32 v199, v200, v199
	v_cndmask_b32_e64 v198, v198, v199, s[50:51]
	v_mul_f32_e32 v199, 0x3e38aa3b, v151
	v_max_f32_e32 v200, v198, v198
	v_max_f32_e32 v199, v200, v199
	v_cndmask_b32_e64 v198, v198, v199, s[52:53]
	ds_bpermute_b32 v199, v175, v198
	v_max_f32_e32 v198, v198, v198
	s_waitcnt lgkmcnt(0)
	v_max_f32_e32 v199, v199, v199
	v_max_f32_e32 v198, v198, v199
	ds_bpermute_b32 v199, v159, v198
	s_waitcnt lgkmcnt(0)
	v_max3_f32 v198, v0, v198, v199
	v_sub_f32_e32 v0, v0, v198
	v_exp_f32_e32 v0, v0
	s_nop 0
	v_mul_f32_e32 v165, v165, v0
	v_pk_mul_f32 v[74:75], v[74:75], v[0:1] op_sel_hi:[1,0]
	v_pk_mul_f32 v[72:73], v[72:73], v[0:1] op_sel_hi:[1,0]
	v_pk_mul_f32 v[70:71], v[70:71], v[0:1] op_sel_hi:[1,0]
	v_pk_mul_f32 v[68:69], v[68:69], v[0:1] op_sel_hi:[1,0]
	v_pk_mul_f32 v[66:67], v[66:67], v[0:1] op_sel_hi:[1,0]
	v_pk_mul_f32 v[64:65], v[64:65], v[0:1] op_sel_hi:[1,0]
	v_pk_mul_f32 v[62:63], v[62:63], v[0:1] op_sel_hi:[1,0]
	v_pk_mul_f32 v[60:61], v[60:61], v[0:1] op_sel_hi:[1,0]
	v_mov_b32_e32 v0, v198
; #define MFMA16(a, b, c) __builtin_amdgcn_mfma_f32_16x16x32_bf16((a), (b), (c), 0, 0, 0)
; DI unsigned pk2(float lo, float hi) { f32x2 v = {lo, hi}; bf16x2_t b = __builtin_convertvector(v, bf16x2_t); return __builtin_bit_cast(unsigned, b); }
; template <int MODE>
; DI void nsa_chunk(const KVFrag& f, int kb, int t, bool selbit, const bf16x8 (&qf)[4][2], f32x4 (&O)[4][4], float (&m)[4], float (&l)[4], int quad, bool online) {
;     ...
;   for (int hh = 0; hh < 4; ++hh) {
;     f32x4 s[2];
; #pragma unroll
;     for (int a = 0; a < 2; ++a) { s[a] = MFMA16(f.k[a][0], qf[hh][0], ((f32x4){0.f, 0.f, 0.f, 0.f})); s[a] = MFMA16(f.k[a][1], qf[hh][1], s[a]); }
;     float mn = m[hh];
;     if (online) {
;       float cm = -1e30f;
; #pragma unroll
;       for (int idx = 0; idx < 8; ++idx) if (val[idx]) cm = fmaxf(cm, s[idx >> 2][idx & 3] * SC);
;       cm = fmaxf(cm, __shfl_xor(cm, 16)); cm = fmaxf(cm, __shfl_xor(cm, 32));
;       mn = fmaxf(mn, cm);
;       const float alpha = __builtin_amdgcn_exp2f(m[hh] - mn);
;       m[hh] = mn; l[hh] *= alpha;
; #pragma unroll
;       for (int dt = 0; dt < 4; ++dt) O[hh][dt] = O[hh][dt] * alpha;
;     }
;     float pv[8]; float ps = 0.f;
; #pragma unroll
;     for (int idx = 0; idx < 8; ++idx) { pv[idx] = val[idx] ? __builtin_amdgcn_exp2f(fmaf(s[idx >> 2][idx & 3], SC, -mn)) : 0.f; ps += pv[idx]; }
;     l[hh] += ps;
;     const bf16x8 pf = mk8((u32x4){pk2(pv[0], pv[1]), pk2(pv[2], pv[3]), pk2(pv[4], pv[5]), pk2(pv[6], pv[7])});
; #pragma unroll
;     for (int dt = 0; dt < 4; ++dt) O[hh][dt] = MFMA16(f.v[dt], pf, O[hh][dt]);
.LBB0_734:
	v_mfma_f32_16x16x32_bf16 v[136:139], v[136:139], v[32:35], v[218:221]
	s_nop 3
	v_pk_fma_f32 v[152:153], v[152:153], s[34:35], v[0:1] op_sel_hi:[1,0,0] neg_lo:[0,0,1] neg_hi:[0,0,1]
	v_pk_fma_f32 v[154:155], v[154:155], s[34:35], v[0:1] op_sel_hi:[1,0,0] neg_lo:[0,0,1] neg_hi:[0,0,1]
	v_pk_fma_f32 v[148:149], v[148:149], s[34:35], v[0:1] op_sel_hi:[1,0,0] neg_lo:[0,0,1] neg_hi:[0,0,1]
	v_pk_fma_f32 v[150:151], v[150:151], s[34:35], v[0:1] op_sel_hi:[1,0,0] neg_lo:[0,0,1] neg_hi:[0,0,1]
	v_mfma_f32_16x16x32_bf16 v[136:139], v[140:143], v[36:39], v[136:139]
	v_exp_f32_e32 v152, v152
	v_exp_f32_e32 v153, v153
	v_exp_f32_e32 v154, v154
	v_mfma_f32_16x16x32_bf16 v[140:143], v[144:147], v[32:35], v[222:225]
	v_exp_f32_e32 v155, v155
	v_exp_f32_e32 v148, v148
	v_exp_f32_e32 v149, v149
	v_exp_f32_e32 v150, v150
	v_exp_f32_e32 v151, v151
	v_cvt_pk_bf16_f32 v198, v152, v153
	v_cvt_pk_bf16_f32 v199, v154, v155
	v_cvt_pk_bf16_f32 v200, v148, v149
	v_cvt_pk_bf16_f32 v201, v150, v151
	v_mfma_f32_16x16x32_bf16 v[132:135], v[132:135], v[36:39], v[140:143]
	s_and_b64 vcc, exec, s[10:11]
	v_mfma_f32_16x16x32_bf16 v[72:75], v[128:131], v[198:201], v[72:75]
	v_mfma_f32_16x16x32_bf16 v[68:71], v[124:127], v[198:201], v[68:71]
	v_mfma_f32_16x16x32_bf16 v[64:67], v[120:123], v[198:201], v[64:67]
	v_mfma_f32_16x16x32_bf16 v[60:63], v[116:119], v[198:201], v[60:63]
	s_cbranch_vccnz .LBB0_736
	v_mul_f32_e32 v140, 0x3e38aa3b, v136
	v_max_f32_e32 v140, 0xf149f2ca, v140
	v_cndmask_b32_e64 v140, v232, v140, s[16:17]
	v_mul_f32_e32 v141, 0x3e38aa3b, v137
	v_max_f32_e32 v141, v140, v141
	v_cndmask_b32_e64 v140, v140, v141, s[18:19]
	v_mul_f32_e32 v141, 0x3e38aa3b, v138
	v_max_f32_e32 v141, v140, v141
	v_cndmask_b32_e64 v140, v140, v141, s[44:45]
	v_mul_f32_e32 v141, 0x3e38aa3b, v139
	v_max_f32_e32 v141, v140, v141
	v_cndmask_b32_e64 v140, v140, v141, s[46:47]
	v_mul_f32_e32 v141, 0x3e38aa3b, v132
	v_max_f32_e32 v141, v140, v141
	v_cndmask_b32_e64 v140, v140, v141, s[14:15]
	v_mul_f32_e32 v141, 0x3e38aa3b, v133
	v_max_f32_e32 v142, v140, v140
	v_max_f32_e32 v141, v142, v141
	v_cndmask_b32_e64 v140, v140, v141, s[48:49]
	v_mul_f32_e32 v141, 0x3e38aa3b, v134
	v_max_f32_e32 v142, v140, v140
	v_max_f32_e32 v141, v142, v141
	v_cndmask_b32_e64 v140, v140, v141, s[50:51]
	v_mul_f32_e32 v141, 0x3e38aa3b, v135
	v_max_f32_e32 v142, v140, v140
	v_max_f32_e32 v141, v142, v141
	v_cndmask_b32_e64 v140, v140, v141, s[52:53]
	ds_bpermute_b32 v141, v175, v140
	v_max_f32_e32 v140, v140, v140
	s_waitcnt lgkmcnt(0)
	v_max_f32_e32 v141, v141, v141
	v_max_f32_e32 v140, v140, v141
	ds_bpermute_b32 v141, v159, v140
	s_waitcnt lgkmcnt(0)
	v_max3_f32 v141, v180, v140, v141
	v_sub_f32_e32 v140, v180, v141
	v_exp_f32_e32 v140, v140
	v_mov_b32_e32 v180, v141
	v_mul_f32_e32 v164, v164, v140
	v_pk_mul_f32 v[58:59], v[58:59], v[140:141] op_sel_hi:[1,0]
	v_pk_mul_f32 v[56:57], v[56:57], v[140:141] op_sel_hi:[1,0]
	v_pk_mul_f32 v[54:55], v[54:55], v[140:141] op_sel_hi:[1,0]
	v_pk_mul_f32 v[52:53], v[52:53], v[140:141] op_sel_hi:[1,0]
	v_pk_mul_f32 v[50:51], v[50:51], v[140:141] op_sel_hi:[1,0]
	v_pk_mul_f32 v[48:49], v[48:49], v[140:141] op_sel_hi:[1,0]
	v_pk_mul_f32 v[46:47], v[46:47], v[140:141] op_sel_hi:[1,0]
	v_pk_mul_f32 v[44:45], v[44:45], v[140:141] op_sel_hi:[1,0]
.LBB0_736:
	v_add_f32_e32 v140, 0, v152
	v_add_f32_e32 v140, v153, v140
	v_add_f32_e32 v140, v154, v140
	v_add_f32_e32 v140, v155, v140
	v_add_f32_e32 v140, v148, v140
	v_add_f32_e32 v140, v149, v140
	v_add_f32_e32 v140, v150, v140
	v_add_f32_e32 v140, v151, v140
	v_add_f32_e32 v165, v165, v140
	v_add_f32_e32 v140, 0, v190
	v_add_f32_e32 v140, v191, v140
	v_add_f32_e32 v140, v192, v140
	v_add_f32_e32 v140, v193, v140
	v_add_f32_e32 v140, v194, v140
	v_add_f32_e32 v140, v195, v140
	v_add_f32_e32 v140, v196, v140
	v_add_f32_e32 v140, v197, v140
	v_add_f32_e32 v166, v166, v140
	v_add_f32_e32 v140, 0, v182
	v_add_f32_e32 v140, v183, v140
	v_add_f32_e32 v140, v184, v140
	v_add_f32_e32 v140, v185, v140
	v_pk_fma_f32 v[136:137], v[136:137], s[34:35], v[180:181] op_sel_hi:[1,0,0] neg_lo:[0,0,1] neg_hi:[0,0,1]
	v_pk_fma_f32 v[138:139], v[138:139], s[34:35], v[180:181] op_sel_hi:[1,0,0] neg_lo:[0,0,1] neg_hi:[0,0,1]
	v_pk_fma_f32 v[132:133], v[132:133], s[34:35], v[180:181] op_sel_hi:[1,0,0] neg_lo:[0,0,1] neg_hi:[0,0,1]
	v_pk_fma_f32 v[134:135], v[134:135], s[34:35], v[180:181] op_sel_hi:[1,0,0] neg_lo:[0,0,1] neg_hi:[0,0,1]
	v_add_f32_e32 v140, v186, v140
	v_add_f32_e32 v140, v187, v140
	v_add_f32_e32 v140, v188, v140
	v_add_f32_e32 v140, v189, v140
	v_add_f32_e32 v167, v167, v140
	v_exp_f32_e32 v136, v136
	v_exp_f32_e32 v137, v137
	v_exp_f32_e32 v138, v138
	v_exp_f32_e32 v139, v139
	v_exp_f32_e32 v140, v132
	v_exp_f32_e32 v141, v133
	v_exp_f32_e32 v142, v134
	v_exp_f32_e32 v143, v135
	v_cvt_pk_bf16_f32 v132, v136, v137
	v_cvt_pk_bf16_f32 v133, v138, v139
	v_cvt_pk_bf16_f32 v134, v140, v141
	v_cvt_pk_bf16_f32 v135, v142, v143
	s_nop 1
	v_mfma_f32_16x16x32_bf16 v[56:59], v[128:131], v[132:135], v[56:59]
	v_add_f32_e32 v128, 0, v136
	v_add_f32_e32 v128, v137, v128
	v_add_f32_e32 v128, v138, v128
	v_mfma_f32_16x16x32_bf16 v[52:55], v[124:127], v[132:135], v[52:55]
	v_add_f32_e32 v124, v139, v128
	v_add_f32_e32 v124, v140, v124
	v_add_f32_e32 v124, v141, v124
	v_mfma_f32_16x16x32_bf16 v[48:51], v[120:123], v[132:135], v[48:51]
	v_add_f32_e32 v120, v142, v124
	v_add_f32_e32 v120, v143, v120
	v_add_f32_e32 v164, v164, v120
	v_mfma_f32_16x16x32_bf16 v[44:47], v[116:119], v[132:135], v[44:47]
; #define MFMA16(a, b, c) __builtin_amdgcn_mfma_f32_16x16x32_bf16((a), (b), (c), 0, 0, 0)
; template <int MODE>
; DI void nsa_chunk(const KVFrag& f, int kb, int t, bool selbit, const bf16x8 (&qf)[4][2], f32x4 (&O)[4][4], float (&m)[4], float (&l)[4], int quad, bool online) {
;   const float SC = 0.125f * 1.44269504089f;
;   bool val[8];
; #pragma unroll
;   for (int idx = 0; idx < 8; ++idx) {
;     const int key = kb + 8 * quad + idx;
;     val[idx] = MODE == 0 ? (selbit && key <= t) : (key <= t && key > t - 512);
;   }
; #pragma unroll
;   for (int hh = 0; hh < 4; ++hh) {
;     f32x4 s[2];
; #pragma unroll
;     for (int a = 0; a < 2; ++a) { s[a] = MFMA16(f.k[a][0], qf[hh][0], ((f32x4){0.f, 0.f, 0.f, 0.f})); s[a] = MFMA16(f.k[a][1], qf[hh][1], s[a]); }
;     float mn = m[hh];
;     if (online) {
;       float cm = -1e30f;
; #pragma unroll
;       for (int idx = 0; idx < 8; ++idx) if (val[idx]) cm = fmaxf(cm, s[idx >> 2][idx & 3] * SC);
;       cm = fmaxf(cm, __shfl_xor(cm, 16)); cm = fmaxf(cm, __shfl_xor(cm, 32));
;       mn = fmaxf(mn, cm);
;       const float alpha = __builtin_amdgcn_exp2f(m[hh] - mn);
;       m[hh] = mn; l[hh] *= alpha;
; #pragma unroll
;       for (int dt = 0; dt < 4; ++dt) O[hh][dt] = O[hh][dt] * alpha;
;     }
; template <int MODE>
; DI void nsa_branch(const bf16_t* __restrict__ Kb, const bf16_t* __restrict__ Vtb, unsigned char* lds, int nb, int t, int cur, unsigned selmask, unsigned umall,
;                    const bf16x8 (&qf)[4][2], f32x4 (&O)[4][4], float (&m)[4], float (&l)[4], bool online) {
;     ...
;     *(u32x4*)(slot1 + ldst) = rb;
;     __syncthreads();
;     rb = *(const u32x4*)(gsrc + (long)kbof(min(n + 3, N - 1)) * gmul);
;     if (won) { KVFrag f; nsa_ldsfrag(f, slot1, qi, quad); nsa_chunk<MODE>(f, j * 64 + 32, t, bit, qf, O, m, l, quad, online); }
.LBB0_737:
	s_min_i32 s14, s54, s55
	s_lshr_b32 s14, s14, 1
	v_add_u32_e32 v116, 0x12600, v161
	s_waitcnt vmcnt(1)
	ds_write_b128 v116, v[108:111]
	s_waitcnt lgkmcnt(0)
	s_barrier
	v_readlane_b32 s14, v216, s14
	s_andn2_b64 vcc, exec, s[0:1]
	s_lshl_b32 s14, s14, 6
	s_or_b32 s14, s14, 32
	s_ashr_i32 s15, s14, 31
	s_lshl_b64 s[14:15], s[14:15], 7
	v_lshl_add_u64 v[108:109], v[168:169], 0, s[14:15]
	global_load_dwordx4 v[108:111], v[108:109], off
	s_cbranch_vccnz .LBB0_726
	v_lshl_or_b32 v181, v181, 6, v174
	v_cmp_le_i32_e32 vcc, v181, v160
	s_and_b64 s[16:17], s[12:13], vcc
	v_cmp_lt_i32_e32 vcc, v181, v160
	v_or_b32_e32 v148, 2, v181
	s_and_b64 s[18:19], s[12:13], vcc
	v_cmp_le_i32_e32 vcc, v148, v160
	v_or_b32_e32 v148, 3, v181
	s_and_b64 s[44:45], s[12:13], vcc
	v_cmp_le_i32_e32 vcc, v148, v160
	v_or_b32_e32 v148, 4, v181
	ds_read_b128 v[136:139], v178
	ds_read_b128 v[140:143], v178 offset:64
	ds_read_b128 v[144:147], v178 offset:576
	ds_read_b128 v[132:135], v178 offset:640
	ds_read_b128 v[128:131], v179
	ds_read_b128 v[124:127], v179 offset:1280
	ds_read_b128 v[120:123], v179 offset:2560
	ds_read_b128 v[116:119], v179 offset:3840
	s_and_b64 s[46:47], s[12:13], vcc
	v_cmp_le_i32_e32 vcc, v148, v160
	v_or_b32_e32 v152, 5, v181
	s_and_b64 s[14:15], s[12:13], vcc
	v_cmp_le_i32_e32 vcc, v152, v160
	v_or_b32_e32 v182, 6, v181
	s_and_b64 s[48:49], s[12:13], vcc
	v_cmp_le_i32_e32 vcc, v182, v160
	v_or_b32_e32 v181, 7, v181
	s_and_b64 s[50:51], s[12:13], vcc
	v_cmp_le_i32_e32 vcc, v181, v160
	s_and_b64 s[12:13], s[12:13], vcc
	s_and_b64 vcc, exec, s[10:11]
	v_mov_b32_e32 v226, 0xff800000
	v_cndmask_b32_e64 v218, v226, 0, s[16:17]
	v_cndmask_b32_e64 v219, v226, 0, s[18:19]
	v_cndmask_b32_e64 v220, v226, 0, s[44:45]
	v_cndmask_b32_e64 v221, v226, 0, s[46:47]
	v_cndmask_b32_e64 v222, v226, 0, s[14:15]
	v_cndmask_b32_e64 v223, v226, 0, s[48:49]
	v_cndmask_b32_e64 v224, v226, 0, s[50:51]
	v_cndmask_b32_e64 v225, v226, 0, s[12:13]
	s_nop 1
	s_waitcnt lgkmcnt(7)
	v_mfma_f32_16x16x32_bf16 v[148:151], v[136:139], v[8:11], v[218:221]
	s_waitcnt lgkmcnt(6)
	v_mfma_f32_16x16x32_bf16 v[152:155], v[140:143], v[12:15], v[148:151]
	s_waitcnt lgkmcnt(5)
	v_mfma_f32_16x16x32_bf16 v[148:151], v[144:147], v[8:11], v[222:225]
	s_waitcnt lgkmcnt(4)
	v_mfma_f32_16x16x32_bf16 v[148:151], v[132:135], v[12:15], v[148:151]
	s_nop 7
	s_cbranch_vccnz .LBB0_740
	v_mul_f32_e32 v181, 0x3e38aa3b, v152
	v_max_f32_e32 v181, 0xf149f2ca, v181
	v_cndmask_b32_e64 v181, v232, v181, s[16:17]
	v_mul_f32_e32 v182, 0x3e38aa3b, v153
	v_max_f32_e32 v182, v181, v182
	v_cndmask_b32_e64 v181, v181, v182, s[18:19]
	v_mul_f32_e32 v182, 0x3e38aa3b, v154
	v_max_f32_e32 v182, v181, v182
	v_cndmask_b32_e64 v181, v181, v182, s[44:45]
	v_mul_f32_e32 v182, 0x3e38aa3b, v155
	v_max_f32_e32 v182, v181, v182
	v_cndmask_b32_e64 v181, v181, v182, s[46:47]
	v_mul_f32_e32 v182, 0x3e38aa3b, v148
	v_max_f32_e32 v182, v181, v182
	v_cndmask_b32_e64 v181, v181, v182, s[14:15]
	v_mul_f32_e32 v182, 0x3e38aa3b, v149
	v_max_f32_e32 v183, v181, v181
	v_max_f32_e32 v182, v183, v182
	v_cndmask_b32_e64 v181, v181, v182, s[48:49]
	v_mul_f32_e32 v182, 0x3e38aa3b, v150
	v_max_f32_e32 v183, v181, v181
	v_max_f32_e32 v182, v183, v182
	v_cndmask_b32_e64 v181, v181, v182, s[50:51]
	v_mul_f32_e32 v182, 0x3e38aa3b, v151
	v_max_f32_e32 v183, v181, v181
	v_max_f32_e32 v182, v183, v182
	v_cndmask_b32_e64 v181, v181, v182, s[12:13]
	ds_bpermute_b32 v182, v175, v181
	v_max_f32_e32 v181, v181, v181
	s_waitcnt lgkmcnt(0)
	v_max_f32_e32 v182, v182, v182
	v_max_f32_e32 v181, v181, v182
	ds_bpermute_b32 v182, v159, v181
	s_waitcnt lgkmcnt(0)
	v_max3_f32 v181, v3, v181, v182
	v_sub_f32_e32 v3, v3, v181
	v_exp_f32_e32 v182, v3
	v_mov_b32_e32 v3, v181
	v_mul_f32_e32 v167, v167, v182
	v_pk_mul_f32 v[106:107], v[106:107], v[182:183] op_sel_hi:[1,0]
	v_pk_mul_f32 v[104:105], v[104:105], v[182:183] op_sel_hi:[1,0]
	v_pk_mul_f32 v[102:103], v[102:103], v[182:183] op_sel_hi:[1,0]
	v_pk_mul_f32 v[100:101], v[100:101], v[182:183] op_sel_hi:[1,0]
	v_pk_mul_f32 v[98:99], v[98:99], v[182:183] op_sel_hi:[1,0]
	v_pk_mul_f32 v[96:97], v[96:97], v[182:183] op_sel_hi:[1,0]
	v_pk_mul_f32 v[94:95], v[94:95], v[182:183] op_sel_hi:[1,0]
	v_pk_mul_f32 v[92:93], v[92:93], v[182:183] op_sel_hi:[1,0]
; #define MFMA16(a, b, c) __builtin_amdgcn_mfma_f32_16x16x32_bf16((a), (b), (c), 0, 0, 0)
; DI unsigned pk2(float lo, float hi) { f32x2 v = {lo, hi}; bf16x2_t b = __builtin_convertvector(v, bf16x2_t); return __builtin_bit_cast(unsigned, b); }
; template <int MODE>
; DI void nsa_chunk(const KVFrag& f, int kb, int t, bool selbit, const bf16x8 (&qf)[4][2], f32x4 (&O)[4][4], float (&m)[4], float (&l)[4], int quad, bool online) {
;     ...
;   for (int hh = 0; hh < 4; ++hh) {
;     f32x4 s[2];
; #pragma unroll
;     for (int a = 0; a < 2; ++a) { s[a] = MFMA16(f.k[a][0], qf[hh][0], ((f32x4){0.f, 0.f, 0.f, 0.f})); s[a] = MFMA16(f.k[a][1], qf[hh][1], s[a]); }
;     float mn = m[hh];
;     if (online) {
;       float cm = -1e30f;
; #pragma unroll
;       for (int idx = 0; idx < 8; ++idx) if (val[idx]) cm = fmaxf(cm, s[idx >> 2][idx & 3] * SC);
;       cm = fmaxf(cm, __shfl_xor(cm, 16)); cm = fmaxf(cm, __shfl_xor(cm, 32));
;       mn = fmaxf(mn, cm);
;       const float alpha = __builtin_amdgcn_exp2f(m[hh] - mn);
;       m[hh] = mn; l[hh] *= alpha;
; #pragma unroll
;       for (int dt = 0; dt < 4; ++dt) O[hh][dt] = O[hh][dt] * alpha;
;     }
;     float pv[8]; float ps = 0.f;
; #pragma unroll
;     for (int idx = 0; idx < 8; ++idx) { pv[idx] = val[idx] ? __builtin_amdgcn_exp2f(fmaf(s[idx >> 2][idx & 3], SC, -mn)) : 0.f; ps += pv[idx]; }
;     l[hh] += ps;
;     const bf16x8 pf = mk8((u32x4){pk2(pv[0], pv[1]), pk2(pv[2], pv[3]), pk2(pv[4], pv[5]), pk2(pv[6], pv[7])});
; #pragma unroll
;     for (int dt = 0; dt < 4; ++dt) O[hh][dt] = MFMA16(f.v[dt], pf, O[hh][dt]);
.LBB0_740:
	v_pk_fma_f32 v[152:153], v[152:153], s[34:35], v[2:3] op_sel:[0,0,1] op_sel_hi:[1,0,1] neg_lo:[0,0,1] neg_hi:[0,0,1]
	v_pk_fma_f32 v[154:155], v[154:155], s[34:35], v[2:3] op_sel:[0,0,1] op_sel_hi:[1,0,1] neg_lo:[0,0,1] neg_hi:[0,0,1]
	s_nop 0
	v_pk_fma_f32 v[148:149], v[148:149], s[34:35], v[2:3] op_sel:[0,0,1] op_sel_hi:[1,0,1] neg_lo:[0,0,1] neg_hi:[0,0,1]
	v_pk_fma_f32 v[150:151], v[150:151], s[34:35], v[2:3] op_sel:[0,0,1] op_sel_hi:[1,0,1] neg_lo:[0,0,1] neg_hi:[0,0,1]
	v_exp_f32_e32 v181, v152
	v_exp_f32_e32 v182, v153
	v_exp_f32_e32 v183, v154
	v_exp_f32_e32 v184, v155
	v_exp_f32_e32 v185, v148
	v_exp_f32_e32 v186, v149
	v_exp_f32_e32 v187, v150
	v_exp_f32_e32 v188, v151
	v_cvt_pk_bf16_f32 v148, v181, v182
	v_cvt_pk_bf16_f32 v149, v183, v184
	v_cvt_pk_bf16_f32 v150, v185, v186
	v_cvt_pk_bf16_f32 v151, v187, v188
	s_and_b64 vcc, exec, s[10:11]
	s_waitcnt lgkmcnt(3)
	v_mfma_f32_16x16x32_bf16 v[104:107], v[128:131], v[148:151], v[104:107]
	s_waitcnt lgkmcnt(2)
	v_mfma_f32_16x16x32_bf16 v[100:103], v[124:127], v[148:151], v[100:103]
	s_waitcnt lgkmcnt(1)
	v_mfma_f32_16x16x32_bf16 v[96:99], v[120:123], v[148:151], v[96:99]
	s_waitcnt lgkmcnt(0)
	v_mfma_f32_16x16x32_bf16 v[92:95], v[116:119], v[148:151], v[92:95]
	v_mfma_f32_16x16x32_bf16 v[148:151], v[136:139], v[16:19], v[218:221]
	v_mfma_f32_16x16x32_bf16 v[152:155], v[140:143], v[20:23], v[148:151]
	v_mfma_f32_16x16x32_bf16 v[148:151], v[144:147], v[16:19], v[222:225]
	v_mfma_f32_16x16x32_bf16 v[148:151], v[132:135], v[20:23], v[148:151]
	s_cbranch_vccnz .LBB0_742
	s_nop 4
	v_mul_f32_e32 v189, 0x3e38aa3b, v152
	v_max_f32_e32 v189, 0xf149f2ca, v189
	v_cndmask_b32_e64 v189, v232, v189, s[16:17]
	v_mul_f32_e32 v190, 0x3e38aa3b, v153
	v_max_f32_e32 v190, v189, v190
	v_cndmask_b32_e64 v189, v189, v190, s[18:19]
	v_mul_f32_e32 v190, 0x3e38aa3b, v154
	v_max_f32_e32 v190, v189, v190
	v_cndmask_b32_e64 v189, v189, v190, s[44:45]
	v_mul_f32_e32 v190, 0x3e38aa3b, v155
	v_max_f32_e32 v190, v189, v190
	v_cndmask_b32_e64 v189, v189, v190, s[46:47]
	v_mul_f32_e32 v190, 0x3e38aa3b, v148
	v_max_f32_e32 v190, v189, v190
	v_cndmask_b32_e64 v189, v189, v190, s[14:15]
	v_mul_f32_e32 v190, 0x3e38aa3b, v149
	v_max_f32_e32 v191, v189, v189
	v_max_f32_e32 v190, v191, v190
	v_cndmask_b32_e64 v189, v189, v190, s[48:49]
	v_mul_f32_e32 v190, 0x3e38aa3b, v150
	v_max_f32_e32 v191, v189, v189
	v_max_f32_e32 v190, v191, v190
	v_cndmask_b32_e64 v189, v189, v190, s[50:51]
	v_mul_f32_e32 v190, 0x3e38aa3b, v151
	v_max_f32_e32 v191, v189, v189
	v_max_f32_e32 v190, v191, v190
	v_cndmask_b32_e64 v189, v189, v190, s[12:13]
	ds_bpermute_b32 v190, v175, v189
	v_max_f32_e32 v189, v189, v189
	s_waitcnt lgkmcnt(0)
	v_max_f32_e32 v190, v190, v190
	v_max_f32_e32 v189, v189, v190
	ds_bpermute_b32 v190, v159, v189
	s_waitcnt lgkmcnt(0)
	v_max3_f32 v189, v2, v189, v190
	v_sub_f32_e32 v2, v2, v189
	v_exp_f32_e32 v2, v2
	s_nop 0
	v_mul_f32_e32 v166, v166, v2
	v_pk_mul_f32 v[90:91], v[90:91], v[2:3] op_sel_hi:[1,0]
	v_pk_mul_f32 v[88:89], v[88:89], v[2:3] op_sel_hi:[1,0]
	v_pk_mul_f32 v[86:87], v[86:87], v[2:3] op_sel_hi:[1,0]
	v_pk_mul_f32 v[84:85], v[84:85], v[2:3] op_sel_hi:[1,0]
	v_pk_mul_f32 v[82:83], v[82:83], v[2:3] op_sel_hi:[1,0]
	v_pk_mul_f32 v[80:81], v[80:81], v[2:3] op_sel_hi:[1,0]
	v_pk_mul_f32 v[78:79], v[78:79], v[2:3] op_sel_hi:[1,0]
	v_pk_mul_f32 v[76:77], v[76:77], v[2:3] op_sel_hi:[1,0]
	v_mov_b32_e32 v2, v189
; #define MFMA16(a, b, c) __builtin_amdgcn_mfma_f32_16x16x32_bf16((a), (b), (c), 0, 0, 0)
; DI unsigned pk2(float lo, float hi) { f32x2 v = {lo, hi}; bf16x2_t b = __builtin_convertvector(v, bf16x2_t); return __builtin_bit_cast(unsigned, b); }
; template <int MODE>
; DI void nsa_chunk(const KVFrag& f, int kb, int t, bool selbit, const bf16x8 (&qf)[4][2], f32x4 (&O)[4][4], float (&m)[4], float (&l)[4], int quad, bool online) {
;     ...
;   for (int hh = 0; hh < 4; ++hh) {
;     f32x4 s[2];
; #pragma unroll
;     for (int a = 0; a < 2; ++a) { s[a] = MFMA16(f.k[a][0], qf[hh][0], ((f32x4){0.f, 0.f, 0.f, 0.f})); s[a] = MFMA16(f.k[a][1], qf[hh][1], s[a]); }
;     float mn = m[hh];
;     if (online) {
;       float cm = -1e30f;
; #pragma unroll
;       for (int idx = 0; idx < 8; ++idx) if (val[idx]) cm = fmaxf(cm, s[idx >> 2][idx & 3] * SC);
;       cm = fmaxf(cm, __shfl_xor(cm, 16)); cm = fmaxf(cm, __shfl_xor(cm, 32));
;       mn = fmaxf(mn, cm);
;       const float alpha = __builtin_amdgcn_exp2f(m[hh] - mn);
;       m[hh] = mn; l[hh] *= alpha;
; #pragma unroll
;       for (int dt = 0; dt < 4; ++dt) O[hh][dt] = O[hh][dt] * alpha;
;     }
;     float pv[8]; float ps = 0.f;
; #pragma unroll
;     for (int idx = 0; idx < 8; ++idx) { pv[idx] = val[idx] ? __builtin_amdgcn_exp2f(fmaf(s[idx >> 2][idx & 3], SC, -mn)) : 0.f; ps += pv[idx]; }
;     l[hh] += ps;
;     const bf16x8 pf = mk8((u32x4){pk2(pv[0], pv[1]), pk2(pv[2], pv[3]), pk2(pv[4], pv[5]), pk2(pv[6], pv[7])});
; #pragma unroll
;     for (int dt = 0; dt < 4; ++dt) O[hh][dt] = MFMA16(f.v[dt], pf, O[hh][dt]);
.LBB0_742:
	s_nop 4
	v_pk_fma_f32 v[152:153], v[152:153], s[34:35], v[2:3] op_sel_hi:[1,0,0] neg_lo:[0,0,1] neg_hi:[0,0,1]
	v_pk_fma_f32 v[154:155], v[154:155], s[34:35], v[2:3] op_sel_hi:[1,0,0] neg_lo:[0,0,1] neg_hi:[0,0,1]
	v_pk_fma_f32 v[148:149], v[148:149], s[34:35], v[2:3] op_sel_hi:[1,0,0] neg_lo:[0,0,1] neg_hi:[0,0,1]
	v_pk_fma_f32 v[150:151], v[150:151], s[34:35], v[2:3] op_sel_hi:[1,0,0] neg_lo:[0,0,1] neg_hi:[0,0,1]
	v_exp_f32_e32 v189, v152
	v_exp_f32_e32 v190, v153
	v_exp_f32_e32 v191, v154
	v_exp_f32_e32 v192, v155
	v_exp_f32_e32 v193, v148
	v_exp_f32_e32 v194, v149
	v_exp_f32_e32 v195, v150
	v_exp_f32_e32 v196, v151
	v_cvt_pk_bf16_f32 v148, v189, v190
	v_cvt_pk_bf16_f32 v149, v191, v192
	v_cvt_pk_bf16_f32 v150, v193, v194
	v_cvt_pk_bf16_f32 v151, v195, v196
	s_and_b64 vcc, exec, s[10:11]
	s_nop 0
	v_mfma_f32_16x16x32_bf16 v[88:91], v[128:131], v[148:151], v[88:91]
	v_mfma_f32_16x16x32_bf16 v[84:87], v[124:127], v[148:151], v[84:87]
	v_mfma_f32_16x16x32_bf16 v[80:83], v[120:123], v[148:151], v[80:83]
	v_mfma_f32_16x16x32_bf16 v[76:79], v[116:119], v[148:151], v[76:79]
	v_mfma_f32_16x16x32_bf16 v[148:151], v[136:139], v[24:27], v[218:221]
	v_mfma_f32_16x16x32_bf16 v[152:155], v[140:143], v[28:31], v[148:151]
	v_mfma_f32_16x16x32_bf16 v[148:151], v[144:147], v[24:27], v[222:225]
	v_mfma_f32_16x16x32_bf16 v[148:151], v[132:135], v[28:31], v[148:151]
	s_cbranch_vccnz .LBB0_744
	s_nop 4
	v_mul_f32_e32 v197, 0x3e38aa3b, v152
	v_max_f32_e32 v197, 0xf149f2ca, v197
	v_cndmask_b32_e64 v197, v232, v197, s[16:17]
	v_mul_f32_e32 v198, 0x3e38aa3b, v153
	v_max_f32_e32 v198, v197, v198
	v_cndmask_b32_e64 v197, v197, v198, s[18:19]
	v_mul_f32_e32 v198, 0x3e38aa3b, v154
	v_max_f32_e32 v198, v197, v198
	v_cndmask_b32_e64 v197, v197, v198, s[44:45]
	v_mul_f32_e32 v198, 0x3e38aa3b, v155
	v_max_f32_e32 v198, v197, v198
	v_cndmask_b32_e64 v197, v197, v198, s[46:47]
	v_mul_f32_e32 v198, 0x3e38aa3b, v148
	v_max_f32_e32 v198, v197, v198
	v_cndmask_b32_e64 v197, v197, v198, s[14:15]
	v_mul_f32_e32 v198, 0x3e38aa3b, v149
	v_max_f32_e32 v199, v197, v197
	v_max_f32_e32 v198, v199, v198
	v_cndmask_b32_e64 v197, v197, v198, s[48:49]
	v_mul_f32_e32 v198, 0x3e38aa3b, v150
	v_max_f32_e32 v199, v197, v197
	v_max_f32_e32 v198, v199, v198
	v_cndmask_b32_e64 v197, v197, v198, s[50:51]
	v_mul_f32_e32 v198, 0x3e38aa3b, v151
	v_max_f32_e32 v199, v197, v197
	v_max_f32_e32 v198, v199, v198
	v_cndmask_b32_e64 v197, v197, v198, s[12:13]
	ds_bpermute_b32 v198, v175, v197
	v_max_f32_e32 v197, v197, v197
	s_waitcnt lgkmcnt(0)
	v_max_f32_e32 v198, v198, v198
	v_max_f32_e32 v197, v197, v198
	ds_bpermute_b32 v198, v159, v197
	s_waitcnt lgkmcnt(0)
	v_max3_f32 v197, v0, v197, v198
	v_sub_f32_e32 v0, v0, v197
	v_exp_f32_e32 v0, v0
	s_nop 0
	v_mul_f32_e32 v165, v165, v0
	v_pk_mul_f32 v[74:75], v[74:75], v[0:1] op_sel_hi:[1,0]
	v_pk_mul_f32 v[72:73], v[72:73], v[0:1] op_sel_hi:[1,0]
	v_pk_mul_f32 v[70:71], v[70:71], v[0:1] op_sel_hi:[1,0]
	v_pk_mul_f32 v[68:69], v[68:69], v[0:1] op_sel_hi:[1,0]
	v_pk_mul_f32 v[66:67], v[66:67], v[0:1] op_sel_hi:[1,0]
	v_pk_mul_f32 v[64:65], v[64:65], v[0:1] op_sel_hi:[1,0]
	v_pk_mul_f32 v[62:63], v[62:63], v[0:1] op_sel_hi:[1,0]
	v_pk_mul_f32 v[60:61], v[60:61], v[0:1] op_sel_hi:[1,0]
	v_mov_b32_e32 v0, v197
.LBB0_744:
	v_mfma_f32_16x16x32_bf16 v[136:139], v[136:139], v[32:35], v[218:221]
	s_nop 3
	v_pk_fma_f32 v[152:153], v[152:153], s[34:35], v[0:1] op_sel_hi:[1,0,0] neg_lo:[0,0,1] neg_hi:[0,0,1]
	v_pk_fma_f32 v[154:155], v[154:155], s[34:35], v[0:1] op_sel_hi:[1,0,0] neg_lo:[0,0,1] neg_hi:[0,0,1]
	v_pk_fma_f32 v[148:149], v[148:149], s[34:35], v[0:1] op_sel_hi:[1,0,0] neg_lo:[0,0,1] neg_hi:[0,0,1]
	v_pk_fma_f32 v[150:151], v[150:151], s[34:35], v[0:1] op_sel_hi:[1,0,0] neg_lo:[0,0,1] neg_hi:[0,0,1]
	v_mfma_f32_16x16x32_bf16 v[136:139], v[140:143], v[36:39], v[136:139]
	v_exp_f32_e32 v152, v152
	v_exp_f32_e32 v153, v153
	v_exp_f32_e32 v154, v154
	v_mfma_f32_16x16x32_bf16 v[140:143], v[144:147], v[32:35], v[222:225]
	v_exp_f32_e32 v155, v155
	v_exp_f32_e32 v148, v148
	v_exp_f32_e32 v149, v149
	v_exp_f32_e32 v150, v150
	v_exp_f32_e32 v151, v151
	v_cvt_pk_bf16_f32 v198, v152, v153
	v_cvt_pk_bf16_f32 v199, v154, v155
	v_cvt_pk_bf16_f32 v200, v148, v149
	v_cvt_pk_bf16_f32 v201, v150, v151
	v_mfma_f32_16x16x32_bf16 v[132:135], v[132:135], v[36:39], v[140:143]
	s_and_b64 vcc, exec, s[10:11]
	v_mfma_f32_16x16x32_bf16 v[72:75], v[128:131], v[198:201], v[72:75]
	v_mfma_f32_16x16x32_bf16 v[68:71], v[124:127], v[198:201], v[68:71]
	v_mfma_f32_16x16x32_bf16 v[64:67], v[120:123], v[198:201], v[64:67]
	v_mfma_f32_16x16x32_bf16 v[60:63], v[116:119], v[198:201], v[60:63]
	s_cbranch_vccnz .LBB0_725
	v_mul_f32_e32 v140, 0x3e38aa3b, v136
	v_max_f32_e32 v140, 0xf149f2ca, v140
	v_cndmask_b32_e64 v140, v232, v140, s[16:17]
	v_mul_f32_e32 v141, 0x3e38aa3b, v137
	v_max_f32_e32 v141, v140, v141
	v_cndmask_b32_e64 v140, v140, v141, s[18:19]
	v_mul_f32_e32 v141, 0x3e38aa3b, v138
	v_max_f32_e32 v141, v140, v141
	v_cndmask_b32_e64 v140, v140, v141, s[44:45]
	v_mul_f32_e32 v141, 0x3e38aa3b, v139
	v_max_f32_e32 v141, v140, v141
	v_cndmask_b32_e64 v140, v140, v141, s[46:47]
	v_mul_f32_e32 v141, 0x3e38aa3b, v132
	v_max_f32_e32 v141, v140, v141
	v_cndmask_b32_e64 v140, v140, v141, s[14:15]
	v_mul_f32_e32 v141, 0x3e38aa3b, v133
	v_max_f32_e32 v142, v140, v140
	v_max_f32_e32 v141, v142, v141
	v_cndmask_b32_e64 v140, v140, v141, s[48:49]
	v_mul_f32_e32 v141, 0x3e38aa3b, v134
	v_max_f32_e32 v142, v140, v140
	v_max_f32_e32 v141, v142, v141
	v_cndmask_b32_e64 v140, v140, v141, s[50:51]
	v_mul_f32_e32 v141, 0x3e38aa3b, v135
	v_max_f32_e32 v142, v140, v140
	v_max_f32_e32 v141, v142, v141
	v_cndmask_b32_e64 v140, v140, v141, s[12:13]
	ds_bpermute_b32 v141, v175, v140
	v_max_f32_e32 v140, v140, v140
	s_waitcnt lgkmcnt(0)
	v_max_f32_e32 v141, v141, v141
	v_max_f32_e32 v140, v140, v141
	ds_bpermute_b32 v141, v159, v140
	s_waitcnt lgkmcnt(0)
	v_max3_f32 v141, v180, v140, v141
	v_sub_f32_e32 v140, v180, v141
	v_exp_f32_e32 v140, v140
	v_mov_b32_e32 v180, v141
	v_mul_f32_e32 v164, v164, v140
	v_pk_mul_f32 v[58:59], v[58:59], v[140:141] op_sel_hi:[1,0]
	v_pk_mul_f32 v[56:57], v[56:57], v[140:141] op_sel_hi:[1,0]
	v_pk_mul_f32 v[54:55], v[54:55], v[140:141] op_sel_hi:[1,0]
	v_pk_mul_f32 v[52:53], v[52:53], v[140:141] op_sel_hi:[1,0]
	v_pk_mul_f32 v[50:51], v[50:51], v[140:141] op_sel_hi:[1,0]
	v_pk_mul_f32 v[48:49], v[48:49], v[140:141] op_sel_hi:[1,0]
	v_pk_mul_f32 v[46:47], v[46:47], v[140:141] op_sel_hi:[1,0]
	v_pk_mul_f32 v[44:45], v[44:45], v[140:141] op_sel_hi:[1,0]
	s_branch .LBB0_725

; #define MFMA16(a, b, c) __builtin_amdgcn_mfma_f32_16x16x32_bf16((a), (b), (c), 0, 0, 0)
; DI unsigned pk2(float lo, float hi) { f32x2 v = {lo, hi}; bf16x2_t b = __builtin_convertvector(v, bf16x2_t); return __builtin_bit_cast(unsigned, b); }
; template <int MODE>
; DI void nsa_chunk(const KVFrag& f, int kb, int t, bool selbit, const bf16x8 (&qf)[4][2], f32x4 (&O)[4][4], float (&m)[4], float (&l)[4], int quad, bool online) {
;     ...
;     float pv[8]; float ps = 0.f;
; #pragma unroll
;     for (int idx = 0; idx < 8; ++idx) { pv[idx] = val[idx] ? __builtin_amdgcn_exp2f(fmaf(s[idx >> 2][idx & 3], SC, -mn)) : 0.f; ps += pv[idx]; }
;     l[hh] += ps;
;     const bf16x8 pf = mk8((u32x4){pk2(pv[0], pv[1]), pk2(pv[2], pv[3]), pk2(pv[4], pv[5]), pk2(pv[6], pv[7])});
; #pragma unroll
;     for (int dt = 0; dt < 4; ++dt) O[hh][dt] = MFMA16(f.v[dt], pf, O[hh][dt]);
.LBB0_755:
	v_add_f32_e32 v136, 0, v148
	v_add_f32_e32 v136, v149, v136
	v_add_f32_e32 v136, v150, v136
	v_add_f32_e32 v136, v151, v136
	v_add_f32_e32 v136, v144, v136
	v_add_f32_e32 v136, v145, v136
	v_add_f32_e32 v136, v146, v136
	v_add_f32_e32 v136, v147, v136
	v_add_f32_e32 v153, v153, v136
	v_add_f32_e32 v136, 0, v188
	v_add_f32_e32 v136, v189, v136
	v_add_f32_e32 v136, v190, v136
	v_add_f32_e32 v136, v191, v136
	v_add_f32_e32 v136, v192, v136
	v_add_f32_e32 v136, v193, v136
	v_add_f32_e32 v136, v194, v136
	v_add_f32_e32 v136, v195, v136
	v_add_f32_e32 v154, v154, v136
	v_add_f32_e32 v136, 0, v180
	v_add_f32_e32 v136, v181, v136
	v_add_f32_e32 v136, v182, v136
	v_add_f32_e32 v136, v183, v136
	v_pk_fma_f32 v[132:133], v[132:133], s[34:35], v[178:179] op_sel:[0,0,1] op_sel_hi:[1,0,1] neg_lo:[0,0,1] neg_hi:[0,0,1]
	v_pk_fma_f32 v[134:135], v[134:135], s[34:35], v[178:179] op_sel:[0,0,1] op_sel_hi:[1,0,1] neg_lo:[0,0,1] neg_hi:[0,0,1]
	v_pk_fma_f32 v[128:129], v[128:129], s[34:35], v[178:179] op_sel:[0,0,1] op_sel_hi:[1,0,1] neg_lo:[0,0,1] neg_hi:[0,0,1]
	v_pk_fma_f32 v[130:131], v[130:131], s[34:35], v[178:179] op_sel:[0,0,1] op_sel_hi:[1,0,1] neg_lo:[0,0,1] neg_hi:[0,0,1]
	v_add_f32_e32 v136, v184, v136
	v_add_f32_e32 v136, v185, v136
	v_add_f32_e32 v136, v186, v136
	v_add_f32_e32 v136, v187, v136
	v_add_f32_e32 v155, v155, v136
	v_exp_f32_e32 v132, v132
	v_exp_f32_e32 v133, v133
	v_exp_f32_e32 v134, v134
	v_exp_f32_e32 v135, v135
	v_exp_f32_e32 v136, v128
	v_exp_f32_e32 v137, v129
	v_exp_f32_e32 v138, v130
	v_exp_f32_e32 v139, v131
	v_cvt_pk_bf16_f32 v128, v132, v133
	v_cvt_pk_bf16_f32 v129, v134, v135
	v_cvt_pk_bf16_f32 v130, v136, v137
	v_cvt_pk_bf16_f32 v131, v138, v139
	s_nop 1
	v_mfma_f32_16x16x32_bf16 v[52:55], v[124:127], v[128:131], v[52:55]
	v_add_f32_e32 v124, 0, v132
	v_add_f32_e32 v124, v133, v124
	v_add_f32_e32 v124, v134, v124
	v_mfma_f32_16x16x32_bf16 v[48:51], v[120:123], v[128:131], v[48:51]
	v_add_f32_e32 v120, v135, v124
	v_add_f32_e32 v120, v136, v120
	v_add_f32_e32 v120, v137, v120
	v_mfma_f32_16x16x32_bf16 v[44:47], v[116:119], v[128:131], v[44:47]
	v_add_f32_e32 v116, v138, v120
	v_add_f32_e32 v116, v139, v116
	v_add_f32_e32 v152, v152, v116
	v_mfma_f32_16x16x32_bf16 v[40:43], v[112:115], v[128:131], v[40:43]

; #define MFMA16(a, b, c) __builtin_amdgcn_mfma_f32_16x16x32_bf16((a), (b), (c), 0, 0, 0)
; template <int MODE>
; DI void nsa_chunk(const KVFrag& f, int kb, int t, bool selbit, const bf16x8 (&qf)[4][2], f32x4 (&O)[4][4], float (&m)[4], float (&l)[4], int quad, bool online) {
;   const float SC = 0.125f * 1.44269504089f;
;   bool val[8];
; #pragma unroll
;   for (int idx = 0; idx < 8; ++idx) {
;     const int key = kb + 8 * quad + idx;
;     val[idx] = MODE == 0 ? (selbit && key <= t) : (key <= t && key > t - 512);
;   }
; #pragma unroll
;   for (int hh = 0; hh < 4; ++hh) {
;     f32x4 s[2];
; #pragma unroll
;     for (int a = 0; a < 2; ++a) { s[a] = MFMA16(f.k[a][0], qf[hh][0], ((f32x4){0.f, 0.f, 0.f, 0.f})); s[a] = MFMA16(f.k[a][1], qf[hh][1], s[a]); }
;     float mn = m[hh];
;     if (online) {
;       float cm = -1e30f;
; #pragma unroll
;       for (int idx = 0; idx < 8; ++idx) if (val[idx]) cm = fmaxf(cm, s[idx >> 2][idx & 3] * SC);
;       cm = fmaxf(cm, __shfl_xor(cm, 16)); cm = fmaxf(cm, __shfl_xor(cm, 32));
;       mn = fmaxf(mn, cm);
;       const float alpha = __builtin_amdgcn_exp2f(m[hh] - mn);
;       m[hh] = mn; l[hh] *= alpha;
; #pragma unroll
;       for (int dt = 0; dt < 4; ++dt) O[hh][dt] = O[hh][dt] * alpha;
;     }
; template <int MODE>
; DI void nsa_branch(const bf16_t* __restrict__ Kb, const bf16_t* __restrict__ Vtb, unsigned char* lds, int nb, int t, int cur, unsigned selmask, unsigned umall,
;                    const bf16x8 (&qf)[4][2], f32x4 (&O)[4][4], float (&m)[4], float (&l)[4], bool online) {
;     ...
;   for (int n = 0; n < N; n += 2) {
;     const int j = blist[n >> 1];
;     const bool won = MODE == 0 ? ((umall >> j) & 1u) != 0 : (j >= cur - 8 && j <= cur);
;     const bool bit = (selmask >> j) & 1u;
;     ra = *(const u32x4*)(gsrc + (long)kbof(min(n + 2, N - 2)) * gmul);
;     if (won) { KVFrag f; nsa_ldsfrag(f, slot0, qi, quad); nsa_chunk<MODE>(f, j * 64, t, bit, qf, O, m, l, quad, online); }
.LBB0_757:
	v_mov_b32_e32 v108, s30
	s_add_i32 s36, s28, -1
	ds_read_b32 v180, v108
	v_min_i32_e32 v108, s36, v168
	v_lshl_add_u32 v108, v108, 1, 32
	v_add_u32_e32 v108, 0x14c00, v108
	ds_read_b32 v108, v108
	s_waitcnt lgkmcnt(1)
	v_cmp_ge_i32_e32 vcc, v180, v156
	v_cmp_le_i32_e64 s[0:1], v180, v170
	v_cndmask_b32_e64 v112, 0, 1, s[44:45]
	s_and_b64 s[54:55], vcc, s[0:1]
	s_waitcnt lgkmcnt(0)
	v_lshlrev_b32_e32 v108, 6, v108
	v_ashrrev_i32_e32 v109, 31, v108
	v_lshlrev_b64 v[108:109], 7, v[108:109]
	v_lshl_add_u64 v[108:109], v[164:165], 0, v[108:109]
	global_load_dwordx4 v[108:111], v[108:109], off
	v_cmp_ne_u32_e64 s[8:9], 1, v112
	s_and_saveexec_b64 s[56:57], s[54:55]
	s_cbranch_execz .LBB0_767
	v_lshl_or_b32 v181, v180, 6, v169
	v_cmp_le_i32_e32 vcc, v181, v160
	v_cmp_gt_i32_e64 s[0:1], v181, v171
	s_and_b64 s[10:11], vcc, s[0:1]
	v_cmp_lt_i32_e32 vcc, v181, v160
	v_cmp_ge_i32_e64 s[0:1], v181, v171
	v_or_b32_e32 v144, 2, v181
	s_and_b64 s[14:15], vcc, s[0:1]
	v_cmp_le_i32_e32 vcc, v144, v160
	v_cmp_gt_i32_e64 s[0:1], v144, v171
	v_or_b32_e32 v144, 3, v181
	s_and_b64 s[18:19], vcc, s[0:1]
	v_cmp_le_i32_e32 vcc, v144, v160
	v_cmp_gt_i32_e64 s[0:1], v144, v171
	v_or_b32_e32 v144, 4, v181
	s_and_b64 s[46:47], vcc, s[0:1]
	v_cmp_le_i32_e32 vcc, v144, v160
	v_cmp_gt_i32_e64 s[0:1], v144, v171
	v_or_b32_e32 v144, 5, v181
	ds_read_b128 v[132:135], v174
	ds_read_b128 v[136:139], v174 offset:64
	ds_read_b128 v[140:143], v174 offset:576
	ds_read_b128 v[128:131], v174 offset:640
	ds_read_b128 v[124:127], v176
	ds_read_b128 v[120:123], v176 offset:1280
	ds_read_b128 v[116:119], v176 offset:2560
	ds_read_b128 v[112:115], v176 offset:3840
	s_and_b64 s[12:13], vcc, s[0:1]
	v_cmp_le_i32_e32 vcc, v144, v160
	v_cmp_gt_i32_e64 s[0:1], v144, v171
	v_or_b32_e32 v148, 6, v181
	s_and_b64 s[16:17], vcc, s[0:1]
	v_cmp_le_i32_e32 vcc, v148, v160
	v_cmp_gt_i32_e64 s[0:1], v148, v171
	v_or_b32_e32 v181, 7, v181
	s_and_b64 s[48:49], vcc, s[0:1]
	v_cmp_le_i32_e32 vcc, v181, v160
	v_cmp_gt_i32_e64 s[0:1], v181, v171
	s_and_b64 s[50:51], vcc, s[0:1]
	s_and_b64 vcc, exec, s[8:9]
	v_mov_b32_e32 v226, 0xff800000
	v_cndmask_b32_e64 v218, v226, 0, s[10:11]
	v_cndmask_b32_e64 v219, v226, 0, s[14:15]
	v_cndmask_b32_e64 v220, v226, 0, s[18:19]
	v_cndmask_b32_e64 v221, v226, 0, s[46:47]
	v_cndmask_b32_e64 v222, v226, 0, s[12:13]
	v_cndmask_b32_e64 v223, v226, 0, s[16:17]
	v_cndmask_b32_e64 v224, v226, 0, s[48:49]
	v_cndmask_b32_e64 v225, v226, 0, s[50:51]
	s_nop 1
	s_waitcnt lgkmcnt(7)
	v_mfma_f32_16x16x32_bf16 v[144:147], v[132:135], v[8:11], v[218:221]
	s_waitcnt lgkmcnt(6)
	v_mfma_f32_16x16x32_bf16 v[148:151], v[136:139], v[12:15], v[144:147]
	s_waitcnt lgkmcnt(5)
	v_mfma_f32_16x16x32_bf16 v[144:147], v[140:143], v[8:11], v[222:225]
	s_waitcnt lgkmcnt(4)
	v_mfma_f32_16x16x32_bf16 v[144:147], v[128:131], v[12:15], v[144:147]
	s_nop 7
	s_cbranch_vccnz .LBB0_760
	v_mul_f32_e32 v181, 0x3e38aa3b, v148
	v_max_f32_e32 v181, 0xf149f2ca, v181
	v_cndmask_b32_e64 v181, v232, v181, s[10:11]
	v_mul_f32_e32 v182, 0x3e38aa3b, v149
	v_max_f32_e32 v182, v181, v182
	v_cndmask_b32_e64 v181, v181, v182, s[14:15]
	v_mul_f32_e32 v182, 0x3e38aa3b, v150
	v_max_f32_e32 v182, v181, v182
	v_cndmask_b32_e64 v181, v181, v182, s[18:19]
	v_mul_f32_e32 v182, 0x3e38aa3b, v151
	v_max_f32_e32 v182, v181, v182
	v_cndmask_b32_e64 v181, v181, v182, s[46:47]
	v_mul_f32_e32 v182, 0x3e38aa3b, v144
	v_max_f32_e32 v182, v181, v182
	v_cndmask_b32_e64 v181, v181, v182, s[12:13]
	v_mul_f32_e32 v182, 0x3e38aa3b, v145
	v_max_f32_e32 v183, v181, v181
	v_max_f32_e32 v182, v183, v182
	v_cndmask_b32_e64 v181, v181, v182, s[16:17]
	v_mul_f32_e32 v182, 0x3e38aa3b, v146
	v_max_f32_e32 v183, v181, v181
	v_max_f32_e32 v182, v183, v182
	v_cndmask_b32_e64 v181, v181, v182, s[48:49]
	v_mul_f32_e32 v182, 0x3e38aa3b, v147
	v_max_f32_e32 v183, v181, v181
	v_max_f32_e32 v182, v183, v182
	v_cndmask_b32_e64 v181, v181, v182, s[50:51]
	ds_bpermute_b32 v182, v175, v181
	v_max_f32_e32 v181, v181, v181
	s_waitcnt lgkmcnt(0)
	v_max_f32_e32 v182, v182, v182
	v_max_f32_e32 v181, v181, v182
	ds_bpermute_b32 v182, v159, v181
	s_waitcnt lgkmcnt(0)
	v_max3_f32 v181, v3, v181, v182
	v_sub_f32_e32 v3, v3, v181
	v_exp_f32_e32 v182, v3
	v_mov_b32_e32 v3, v181
	v_mul_f32_e32 v155, v155, v182
	v_pk_mul_f32 v[102:103], v[102:103], v[182:183] op_sel_hi:[1,0]
	v_pk_mul_f32 v[100:101], v[100:101], v[182:183] op_sel_hi:[1,0]
	v_pk_mul_f32 v[98:99], v[98:99], v[182:183] op_sel_hi:[1,0]
	v_pk_mul_f32 v[96:97], v[96:97], v[182:183] op_sel_hi:[1,0]
	v_pk_mul_f32 v[94:95], v[94:95], v[182:183] op_sel_hi:[1,0]
	v_pk_mul_f32 v[92:93], v[92:93], v[182:183] op_sel_hi:[1,0]
	v_pk_mul_f32 v[90:91], v[90:91], v[182:183] op_sel_hi:[1,0]
	v_pk_mul_f32 v[88:89], v[88:89], v[182:183] op_sel_hi:[1,0]
; #define MFMA16(a, b, c) __builtin_amdgcn_mfma_f32_16x16x32_bf16((a), (b), (c), 0, 0, 0)
; DI unsigned pk2(float lo, float hi) { f32x2 v = {lo, hi}; bf16x2_t b = __builtin_convertvector(v, bf16x2_t); return __builtin_bit_cast(unsigned, b); }
; template <int MODE>
; DI void nsa_chunk(const KVFrag& f, int kb, int t, bool selbit, const bf16x8 (&qf)[4][2], f32x4 (&O)[4][4], float (&m)[4], float (&l)[4], int quad, bool online) {
;     ...
;   for (int hh = 0; hh < 4; ++hh) {
;     f32x4 s[2];
; #pragma unroll
;     for (int a = 0; a < 2; ++a) { s[a] = MFMA16(f.k[a][0], qf[hh][0], ((f32x4){0.f, 0.f, 0.f, 0.f})); s[a] = MFMA16(f.k[a][1], qf[hh][1], s[a]); }
;     float mn = m[hh];
;     if (online) {
;       float cm = -1e30f;
; #pragma unroll
;       for (int idx = 0; idx < 8; ++idx) if (val[idx]) cm = fmaxf(cm, s[idx >> 2][idx & 3] * SC);
;       cm = fmaxf(cm, __shfl_xor(cm, 16)); cm = fmaxf(cm, __shfl_xor(cm, 32));
;       mn = fmaxf(mn, cm);
;       const float alpha = __builtin_amdgcn_exp2f(m[hh] - mn);
;       m[hh] = mn; l[hh] *= alpha;
; #pragma unroll
;       for (int dt = 0; dt < 4; ++dt) O[hh][dt] = O[hh][dt] * alpha;
;     }
;     float pv[8]; float ps = 0.f;
; #pragma unroll
;     for (int idx = 0; idx < 8; ++idx) { pv[idx] = val[idx] ? __builtin_amdgcn_exp2f(fmaf(s[idx >> 2][idx & 3], SC, -mn)) : 0.f; ps += pv[idx]; }
;     l[hh] += ps;
;     const bf16x8 pf = mk8((u32x4){pk2(pv[0], pv[1]), pk2(pv[2], pv[3]), pk2(pv[4], pv[5]), pk2(pv[6], pv[7])});
; #pragma unroll
;     for (int dt = 0; dt < 4; ++dt) O[hh][dt] = MFMA16(f.v[dt], pf, O[hh][dt]);
.LBB0_760:
	v_pk_fma_f32 v[148:149], v[148:149], s[34:35], v[2:3] op_sel:[0,0,1] op_sel_hi:[1,0,1] neg_lo:[0,0,1] neg_hi:[0,0,1]
	v_pk_fma_f32 v[150:151], v[150:151], s[34:35], v[2:3] op_sel:[0,0,1] op_sel_hi:[1,0,1] neg_lo:[0,0,1] neg_hi:[0,0,1]
	s_nop 2
	v_pk_fma_f32 v[144:145], v[144:145], s[34:35], v[2:3] op_sel:[0,0,1] op_sel_hi:[1,0,1] neg_lo:[0,0,1] neg_hi:[0,0,1]
	v_pk_fma_f32 v[146:147], v[146:147], s[34:35], v[2:3] op_sel:[0,0,1] op_sel_hi:[1,0,1] neg_lo:[0,0,1] neg_hi:[0,0,1]
	v_exp_f32_e32 v181, v148
	v_exp_f32_e32 v182, v149
	v_exp_f32_e32 v183, v150
	v_exp_f32_e32 v184, v151
	v_exp_f32_e32 v185, v144
	v_exp_f32_e32 v186, v145
	v_exp_f32_e32 v187, v146
	v_exp_f32_e32 v188, v147
	v_cvt_pk_bf16_f32 v144, v181, v182
	v_cvt_pk_bf16_f32 v145, v183, v184
	v_cvt_pk_bf16_f32 v146, v185, v186
	v_cvt_pk_bf16_f32 v147, v187, v188
	s_and_b64 vcc, exec, s[8:9]
	s_waitcnt lgkmcnt(3)
	v_mfma_f32_16x16x32_bf16 v[100:103], v[124:127], v[144:147], v[100:103]
	s_waitcnt lgkmcnt(2)
	v_mfma_f32_16x16x32_bf16 v[96:99], v[120:123], v[144:147], v[96:99]
	s_waitcnt lgkmcnt(1)
	v_mfma_f32_16x16x32_bf16 v[92:95], v[116:119], v[144:147], v[92:95]
	s_waitcnt lgkmcnt(0)
	v_mfma_f32_16x16x32_bf16 v[88:91], v[112:115], v[144:147], v[88:91]
	v_mfma_f32_16x16x32_bf16 v[144:147], v[132:135], v[16:19], v[218:221]
	v_mfma_f32_16x16x32_bf16 v[148:151], v[136:139], v[20:23], v[144:147]
	v_mfma_f32_16x16x32_bf16 v[144:147], v[140:143], v[16:19], v[222:225]
	v_mfma_f32_16x16x32_bf16 v[144:147], v[128:131], v[20:23], v[144:147]
	s_cbranch_vccnz .LBB0_762
	s_nop 4
	v_mul_f32_e32 v189, 0x3e38aa3b, v148
	v_max_f32_e32 v189, 0xf149f2ca, v189
	v_cndmask_b32_e64 v189, v232, v189, s[10:11]
	v_mul_f32_e32 v190, 0x3e38aa3b, v149
	v_max_f32_e32 v190, v189, v190
	v_cndmask_b32_e64 v189, v189, v190, s[14:15]
	v_mul_f32_e32 v190, 0x3e38aa3b, v150
	v_max_f32_e32 v190, v189, v190
	v_cndmask_b32_e64 v189, v189, v190, s[18:19]
	v_mul_f32_e32 v190, 0x3e38aa3b, v151
	v_max_f32_e32 v190, v189, v190
	v_cndmask_b32_e64 v189, v189, v190, s[46:47]
	v_mul_f32_e32 v190, 0x3e38aa3b, v144
	v_max_f32_e32 v190, v189, v190
	v_cndmask_b32_e64 v189, v189, v190, s[12:13]
	v_mul_f32_e32 v190, 0x3e38aa3b, v145
	v_max_f32_e32 v191, v189, v189
	v_max_f32_e32 v190, v191, v190
	v_cndmask_b32_e64 v189, v189, v190, s[16:17]
	v_mul_f32_e32 v190, 0x3e38aa3b, v146
	v_max_f32_e32 v191, v189, v189
	v_max_f32_e32 v190, v191, v190
	v_cndmask_b32_e64 v189, v189, v190, s[48:49]
	v_mul_f32_e32 v190, 0x3e38aa3b, v147
	v_max_f32_e32 v191, v189, v189
	v_max_f32_e32 v190, v191, v190
	v_cndmask_b32_e64 v189, v189, v190, s[50:51]
	ds_bpermute_b32 v190, v175, v189
	v_max_f32_e32 v189, v189, v189
	s_waitcnt lgkmcnt(0)
	v_max_f32_e32 v190, v190, v190
	v_max_f32_e32 v189, v189, v190
	ds_bpermute_b32 v190, v159, v189
	s_waitcnt lgkmcnt(0)
	v_max3_f32 v189, v2, v189, v190
	v_sub_f32_e32 v2, v2, v189
	v_exp_f32_e32 v2, v2
	s_nop 0
	v_mul_f32_e32 v154, v154, v2
	v_pk_mul_f32 v[86:87], v[86:87], v[2:3] op_sel_hi:[1,0]
	v_pk_mul_f32 v[84:85], v[84:85], v[2:3] op_sel_hi:[1,0]
	v_pk_mul_f32 v[82:83], v[82:83], v[2:3] op_sel_hi:[1,0]
	v_pk_mul_f32 v[80:81], v[80:81], v[2:3] op_sel_hi:[1,0]
	v_pk_mul_f32 v[78:79], v[78:79], v[2:3] op_sel_hi:[1,0]
	v_pk_mul_f32 v[76:77], v[76:77], v[2:3] op_sel_hi:[1,0]
	v_pk_mul_f32 v[74:75], v[74:75], v[2:3] op_sel_hi:[1,0]
	v_pk_mul_f32 v[72:73], v[72:73], v[2:3] op_sel_hi:[1,0]
	v_mov_b32_e32 v2, v189
.LBB0_762:
	s_nop 4
	v_pk_fma_f32 v[148:149], v[148:149], s[34:35], v[2:3] op_sel_hi:[1,0,0] neg_lo:[0,0,1] neg_hi:[0,0,1]
	v_pk_fma_f32 v[150:151], v[150:151], s[34:35], v[2:3] op_sel_hi:[1,0,0] neg_lo:[0,0,1] neg_hi:[0,0,1]
	v_pk_fma_f32 v[144:145], v[144:145], s[34:35], v[2:3] op_sel_hi:[1,0,0] neg_lo:[0,0,1] neg_hi:[0,0,1]
	v_pk_fma_f32 v[146:147], v[146:147], s[34:35], v[2:3] op_sel_hi:[1,0,0] neg_lo:[0,0,1] neg_hi:[0,0,1]
	v_exp_f32_e32 v189, v148
	v_exp_f32_e32 v190, v149
	v_exp_f32_e32 v191, v150
	v_exp_f32_e32 v192, v151
	v_exp_f32_e32 v193, v144
	v_exp_f32_e32 v194, v145
	v_exp_f32_e32 v195, v146
	v_exp_f32_e32 v196, v147
	v_cvt_pk_bf16_f32 v144, v189, v190
	v_cvt_pk_bf16_f32 v145, v191, v192
	v_cvt_pk_bf16_f32 v146, v193, v194
	v_cvt_pk_bf16_f32 v147, v195, v196
	s_and_b64 vcc, exec, s[8:9]
	s_nop 0
	v_mfma_f32_16x16x32_bf16 v[84:87], v[124:127], v[144:147], v[84:87]
	v_mfma_f32_16x16x32_bf16 v[80:83], v[120:123], v[144:147], v[80:83]
	v_mfma_f32_16x16x32_bf16 v[76:79], v[116:119], v[144:147], v[76:79]
	v_mfma_f32_16x16x32_bf16 v[72:75], v[112:115], v[144:147], v[72:75]
	v_mfma_f32_16x16x32_bf16 v[144:147], v[132:135], v[24:27], v[218:221]
	v_mfma_f32_16x16x32_bf16 v[148:151], v[136:139], v[28:31], v[144:147]
	v_mfma_f32_16x16x32_bf16 v[144:147], v[140:143], v[24:27], v[222:225]
	v_mfma_f32_16x16x32_bf16 v[144:147], v[128:131], v[28:31], v[144:147]
	s_cbranch_vccnz .LBB0_764
	s_nop 4
	v_mul_f32_e32 v197, 0x3e38aa3b, v148
	v_max_f32_e32 v197, 0xf149f2ca, v197
	v_cndmask_b32_e64 v197, v232, v197, s[10:11]
	v_mul_f32_e32 v198, 0x3e38aa3b, v149
	v_max_f32_e32 v198, v197, v198
	v_cndmask_b32_e64 v197, v197, v198, s[14:15]
	v_mul_f32_e32 v198, 0x3e38aa3b, v150
	v_max_f32_e32 v198, v197, v198
	v_cndmask_b32_e64 v197, v197, v198, s[18:19]
	v_mul_f32_e32 v198, 0x3e38aa3b, v151
	v_max_f32_e32 v198, v197, v198
	v_cndmask_b32_e64 v197, v197, v198, s[46:47]
	v_mul_f32_e32 v198, 0x3e38aa3b, v144
	v_max_f32_e32 v198, v197, v198
	v_cndmask_b32_e64 v197, v197, v198, s[12:13]
	v_mul_f32_e32 v198, 0x3e38aa3b, v145
	v_max_f32_e32 v199, v197, v197
	v_max_f32_e32 v198, v199, v198
	v_cndmask_b32_e64 v197, v197, v198, s[16:17]
	v_mul_f32_e32 v198, 0x3e38aa3b, v146
	v_max_f32_e32 v199, v197, v197
	v_max_f32_e32 v198, v199, v198
	v_cndmask_b32_e64 v197, v197, v198, s[48:49]
	v_mul_f32_e32 v198, 0x3e38aa3b, v147
	v_max_f32_e32 v199, v197, v197
	v_max_f32_e32 v198, v199, v198
	v_cndmask_b32_e64 v197, v197, v198, s[50:51]
	ds_bpermute_b32 v198, v175, v197
	v_max_f32_e32 v197, v197, v197
	s_waitcnt lgkmcnt(0)
	v_max_f32_e32 v198, v198, v198
	v_max_f32_e32 v197, v197, v198
	ds_bpermute_b32 v198, v159, v197
	s_waitcnt lgkmcnt(0)
	v_max3_f32 v197, v0, v197, v198
	v_sub_f32_e32 v0, v0, v197
	v_exp_f32_e32 v0, v0
	s_nop 0
	v_mul_f32_e32 v153, v153, v0
	v_pk_mul_f32 v[70:71], v[70:71], v[0:1] op_sel_hi:[1,0]
	v_pk_mul_f32 v[68:69], v[68:69], v[0:1] op_sel_hi:[1,0]
	v_pk_mul_f32 v[66:67], v[66:67], v[0:1] op_sel_hi:[1,0]
	v_pk_mul_f32 v[64:65], v[64:65], v[0:1] op_sel_hi:[1,0]
	v_pk_mul_f32 v[62:63], v[62:63], v[0:1] op_sel_hi:[1,0]
	v_pk_mul_f32 v[60:61], v[60:61], v[0:1] op_sel_hi:[1,0]
	v_pk_mul_f32 v[58:59], v[58:59], v[0:1] op_sel_hi:[1,0]
	v_pk_mul_f32 v[56:57], v[56:57], v[0:1] op_sel_hi:[1,0]
	v_mov_b32_e32 v0, v197
; #define MFMA16(a, b, c) __builtin_amdgcn_mfma_f32_16x16x32_bf16((a), (b), (c), 0, 0, 0)
; DI unsigned pk2(float lo, float hi) { f32x2 v = {lo, hi}; bf16x2_t b = __builtin_convertvector(v, bf16x2_t); return __builtin_bit_cast(unsigned, b); }
; template <int MODE>
; DI void nsa_chunk(const KVFrag& f, int kb, int t, bool selbit, const bf16x8 (&qf)[4][2], f32x4 (&O)[4][4], float (&m)[4], float (&l)[4], int quad, bool online) {
;     ...
;   for (int hh = 0; hh < 4; ++hh) {
;     f32x4 s[2];
; #pragma unroll
;     for (int a = 0; a < 2; ++a) { s[a] = MFMA16(f.k[a][0], qf[hh][0], ((f32x4){0.f, 0.f, 0.f, 0.f})); s[a] = MFMA16(f.k[a][1], qf[hh][1], s[a]); }
;     float mn = m[hh];
;     if (online) {
;       float cm = -1e30f;
; #pragma unroll
;       for (int idx = 0; idx < 8; ++idx) if (val[idx]) cm = fmaxf(cm, s[idx >> 2][idx & 3] * SC);
;       cm = fmaxf(cm, __shfl_xor(cm, 16)); cm = fmaxf(cm, __shfl_xor(cm, 32));
;       mn = fmaxf(mn, cm);
;       const float alpha = __builtin_amdgcn_exp2f(m[hh] - mn);
;       m[hh] = mn; l[hh] *= alpha;
; #pragma unroll
;       for (int dt = 0; dt < 4; ++dt) O[hh][dt] = O[hh][dt] * alpha;
;     }
;     float pv[8]; float ps = 0.f;
; #pragma unroll
;     for (int idx = 0; idx < 8; ++idx) { pv[idx] = val[idx] ? __builtin_amdgcn_exp2f(fmaf(s[idx >> 2][idx & 3], SC, -mn)) : 0.f; ps += pv[idx]; }
;     l[hh] += ps;
;     const bf16x8 pf = mk8((u32x4){pk2(pv[0], pv[1]), pk2(pv[2], pv[3]), pk2(pv[4], pv[5]), pk2(pv[6], pv[7])});
; #pragma unroll
;     for (int dt = 0; dt < 4; ++dt) O[hh][dt] = MFMA16(f.v[dt], pf, O[hh][dt]);
.LBB0_764:
	v_mfma_f32_16x16x32_bf16 v[132:135], v[132:135], v[32:35], v[218:221]
	s_nop 3
	v_pk_fma_f32 v[148:149], v[148:149], s[34:35], v[0:1] op_sel_hi:[1,0,0] neg_lo:[0,0,1] neg_hi:[0,0,1]
	v_pk_fma_f32 v[150:151], v[150:151], s[34:35], v[0:1] op_sel_hi:[1,0,0] neg_lo:[0,0,1] neg_hi:[0,0,1]
	v_pk_fma_f32 v[144:145], v[144:145], s[34:35], v[0:1] op_sel_hi:[1,0,0] neg_lo:[0,0,1] neg_hi:[0,0,1]
	v_pk_fma_f32 v[146:147], v[146:147], s[34:35], v[0:1] op_sel_hi:[1,0,0] neg_lo:[0,0,1] neg_hi:[0,0,1]
	v_mfma_f32_16x16x32_bf16 v[132:135], v[136:139], v[36:39], v[132:135]
	v_exp_f32_e32 v148, v148
	v_exp_f32_e32 v149, v149
	v_exp_f32_e32 v150, v150
	v_mfma_f32_16x16x32_bf16 v[136:139], v[140:143], v[32:35], v[222:225]
	v_exp_f32_e32 v151, v151
	v_exp_f32_e32 v144, v144
	v_exp_f32_e32 v145, v145
	v_exp_f32_e32 v146, v146
	v_exp_f32_e32 v147, v147
	v_cvt_pk_bf16_f32 v198, v148, v149
	v_cvt_pk_bf16_f32 v199, v150, v151
	v_cvt_pk_bf16_f32 v200, v144, v145
	v_cvt_pk_bf16_f32 v201, v146, v147
	v_mfma_f32_16x16x32_bf16 v[128:131], v[128:131], v[36:39], v[136:139]
	s_and_b64 vcc, exec, s[8:9]
	v_mfma_f32_16x16x32_bf16 v[68:71], v[124:127], v[198:201], v[68:71]
	v_mfma_f32_16x16x32_bf16 v[64:67], v[120:123], v[198:201], v[64:67]
	v_mfma_f32_16x16x32_bf16 v[60:63], v[116:119], v[198:201], v[60:63]
	v_mfma_f32_16x16x32_bf16 v[56:59], v[112:115], v[198:201], v[56:59]
	s_cbranch_vccnz .LBB0_766
	v_mul_f32_e32 v136, 0x3e38aa3b, v132
	v_max_f32_e32 v136, 0xf149f2ca, v136
	v_cndmask_b32_e64 v136, v232, v136, s[10:11]
	v_mul_f32_e32 v137, 0x3e38aa3b, v133
	v_max_f32_e32 v137, v136, v137
	v_cndmask_b32_e64 v136, v136, v137, s[14:15]
	v_mul_f32_e32 v137, 0x3e38aa3b, v134
	v_max_f32_e32 v137, v136, v137
	v_cndmask_b32_e64 v136, v136, v137, s[18:19]
	v_mul_f32_e32 v137, 0x3e38aa3b, v135
	v_max_f32_e32 v137, v136, v137
	v_cndmask_b32_e64 v136, v136, v137, s[46:47]
	v_mul_f32_e32 v137, 0x3e38aa3b, v128
	v_max_f32_e32 v137, v136, v137
	v_cndmask_b32_e64 v136, v136, v137, s[12:13]
	v_mul_f32_e32 v137, 0x3e38aa3b, v129
	v_max_f32_e32 v138, v136, v136
	v_max_f32_e32 v137, v138, v137
	v_cndmask_b32_e64 v136, v136, v137, s[16:17]
	v_mul_f32_e32 v137, 0x3e38aa3b, v130
	v_max_f32_e32 v138, v136, v136
	v_max_f32_e32 v137, v138, v137
	v_cndmask_b32_e64 v136, v136, v137, s[48:49]
	v_mul_f32_e32 v137, 0x3e38aa3b, v131
	v_max_f32_e32 v138, v136, v136
	v_max_f32_e32 v137, v138, v137
	v_cndmask_b32_e64 v136, v136, v137, s[50:51]
	ds_bpermute_b32 v137, v175, v136
	v_max_f32_e32 v136, v136, v136
	s_waitcnt lgkmcnt(0)
	v_max_f32_e32 v137, v137, v137
	v_max_f32_e32 v136, v136, v137
	ds_bpermute_b32 v137, v159, v136
	s_waitcnt lgkmcnt(0)
	v_max3_f32 v137, v179, v136, v137
	v_sub_f32_e32 v136, v179, v137
	v_exp_f32_e32 v136, v136
	v_mov_b32_e32 v179, v137
	v_mul_f32_e32 v152, v152, v136
	v_pk_mul_f32 v[54:55], v[54:55], v[136:137] op_sel_hi:[1,0]
	v_pk_mul_f32 v[52:53], v[52:53], v[136:137] op_sel_hi:[1,0]
	v_pk_mul_f32 v[50:51], v[50:51], v[136:137] op_sel_hi:[1,0]
	v_pk_mul_f32 v[48:49], v[48:49], v[136:137] op_sel_hi:[1,0]
	v_pk_mul_f32 v[46:47], v[46:47], v[136:137] op_sel_hi:[1,0]
	v_pk_mul_f32 v[44:45], v[44:45], v[136:137] op_sel_hi:[1,0]
	v_pk_mul_f32 v[42:43], v[42:43], v[136:137] op_sel_hi:[1,0]
	v_pk_mul_f32 v[40:41], v[40:41], v[136:137] op_sel_hi:[1,0]
.LBB0_766:
	v_add_f32_e32 v136, 0, v148
	v_add_f32_e32 v136, v149, v136
	v_add_f32_e32 v136, v150, v136
	v_add_f32_e32 v136, v151, v136
	v_add_f32_e32 v136, v144, v136
	v_add_f32_e32 v136, v145, v136
	v_add_f32_e32 v136, v146, v136
	v_add_f32_e32 v136, v147, v136
	v_add_f32_e32 v153, v153, v136
	v_add_f32_e32 v136, 0, v189
	v_add_f32_e32 v136, v190, v136
	v_add_f32_e32 v136, v191, v136
	v_add_f32_e32 v136, v192, v136
	v_add_f32_e32 v136, v193, v136
	v_add_f32_e32 v136, v194, v136
	v_add_f32_e32 v136, v195, v136
	v_add_f32_e32 v136, v196, v136
	v_add_f32_e32 v154, v154, v136
	v_add_f32_e32 v136, 0, v181
	v_add_f32_e32 v136, v182, v136
	v_add_f32_e32 v136, v183, v136
	v_add_f32_e32 v136, v184, v136
	v_pk_fma_f32 v[132:133], v[132:133], s[34:35], v[178:179] op_sel:[0,0,1] op_sel_hi:[1,0,1] neg_lo:[0,0,1] neg_hi:[0,0,1]
	v_pk_fma_f32 v[134:135], v[134:135], s[34:35], v[178:179] op_sel:[0,0,1] op_sel_hi:[1,0,1] neg_lo:[0,0,1] neg_hi:[0,0,1]
	v_pk_fma_f32 v[128:129], v[128:129], s[34:35], v[178:179] op_sel:[0,0,1] op_sel_hi:[1,0,1] neg_lo:[0,0,1] neg_hi:[0,0,1]
	v_pk_fma_f32 v[130:131], v[130:131], s[34:35], v[178:179] op_sel:[0,0,1] op_sel_hi:[1,0,1] neg_lo:[0,0,1] neg_hi:[0,0,1]
	v_add_f32_e32 v136, v185, v136
	v_add_f32_e32 v136, v186, v136
	v_add_f32_e32 v136, v187, v136
	v_add_f32_e32 v136, v188, v136
	v_add_f32_e32 v155, v155, v136
	v_exp_f32_e32 v132, v132
	v_exp_f32_e32 v133, v133
	v_exp_f32_e32 v134, v134
	v_exp_f32_e32 v135, v135
	v_exp_f32_e32 v136, v128
	v_exp_f32_e32 v137, v129
	v_exp_f32_e32 v138, v130
	v_exp_f32_e32 v139, v131
	v_cvt_pk_bf16_f32 v128, v132, v133
	v_cvt_pk_bf16_f32 v129, v134, v135
	v_cvt_pk_bf16_f32 v130, v136, v137
	v_cvt_pk_bf16_f32 v131, v138, v139
	s_nop 1
	v_mfma_f32_16x16x32_bf16 v[52:55], v[124:127], v[128:131], v[52:55]
	v_add_f32_e32 v124, 0, v132
	v_add_f32_e32 v124, v133, v124
	v_add_f32_e32 v124, v134, v124
	v_mfma_f32_16x16x32_bf16 v[48:51], v[120:123], v[128:131], v[48:51]
	v_add_f32_e32 v120, v135, v124
	v_add_f32_e32 v120, v136, v120
	v_add_f32_e32 v120, v137, v120
	v_mfma_f32_16x16x32_bf16 v[44:47], v[116:119], v[128:131], v[44:47]
	v_add_f32_e32 v116, v138, v120
	v_add_f32_e32 v116, v139, v116
	v_add_f32_e32 v152, v152, v116
	v_mfma_f32_16x16x32_bf16 v[40:43], v[112:115], v[128:131], v[40:43]
; #define MFMA16(a, b, c) __builtin_amdgcn_mfma_f32_16x16x32_bf16((a), (b), (c), 0, 0, 0)
; template <int MODE>
; DI void nsa_chunk(const KVFrag& f, int kb, int t, bool selbit, const bf16x8 (&qf)[4][2], f32x4 (&O)[4][4], float (&m)[4], float (&l)[4], int quad, bool online) {
;   const float SC = 0.125f * 1.44269504089f;
;   bool val[8];
; #pragma unroll
;   for (int idx = 0; idx < 8; ++idx) {
;     const int key = kb + 8 * quad + idx;
;     val[idx] = MODE == 0 ? (selbit && key <= t) : (key <= t && key > t - 512);
;   }
; #pragma unroll
;   for (int hh = 0; hh < 4; ++hh) {
;     f32x4 s[2];
; #pragma unroll
;     for (int a = 0; a < 2; ++a) { s[a] = MFMA16(f.k[a][0], qf[hh][0], ((f32x4){0.f, 0.f, 0.f, 0.f})); s[a] = MFMA16(f.k[a][1], qf[hh][1], s[a]); }
;     float mn = m[hh];
;     if (online) {
;       float cm = -1e30f;
; #pragma unroll
;       for (int idx = 0; idx < 8; ++idx) if (val[idx]) cm = fmaxf(cm, s[idx >> 2][idx & 3] * SC);
;       cm = fmaxf(cm, __shfl_xor(cm, 16)); cm = fmaxf(cm, __shfl_xor(cm, 32));
;       mn = fmaxf(mn, cm);
;       const float alpha = __builtin_amdgcn_exp2f(m[hh] - mn);
;       m[hh] = mn; l[hh] *= alpha;
; #pragma unroll
;       for (int dt = 0; dt < 4; ++dt) O[hh][dt] = O[hh][dt] * alpha;
;     }
; template <int MODE>
; DI void nsa_branch(const bf16_t* __restrict__ Kb, const bf16_t* __restrict__ Vtb, unsigned char* lds, int nb, int t, int cur, unsigned selmask, unsigned umall,
;                    const bf16x8 (&qf)[4][2], f32x4 (&O)[4][4], float (&m)[4], float (&l)[4], bool online) {
;     ...
;     *(u32x4*)(slot1 + ldst) = rb;
;     __syncthreads();
;     rb = *(const u32x4*)(gsrc + (long)kbof(min(n + 3, N - 1)) * gmul);
;     if (won) { KVFrag f; nsa_ldsfrag(f, slot1, qi, quad); nsa_chunk<MODE>(f, j * 64 + 32, t, bit, qf, O, m, l, quad, online); }
.LBB0_767:
	s_or_b64 exec, exec, s[56:57]
	v_add_u32_e32 v112, 0x12600, v161
	s_waitcnt vmcnt(1)
	ds_write_b128 v112, v[104:107]
	v_min_i32_e32 v104, s28, v172
	v_lshlrev_b32_e32 v104, 1, v104
	v_and_b32_e32 v104, -4, v104
	v_add_u32_e32 v104, 32, v104
	v_add_u32_e32 v104, 0x14c00, v104
	s_waitcnt lgkmcnt(0)
	s_barrier
	ds_read_b32 v104, v104
	s_waitcnt lgkmcnt(0)
	v_lshl_or_b32 v104, v104, 6, 32
	v_ashrrev_i32_e32 v105, 31, v104
	v_lshlrev_b64 v[104:105], 7, v[104:105]
	v_lshl_add_u64 v[104:105], v[164:165], 0, v[104:105]
	global_load_dwordx4 v[104:107], v[104:105], off
	s_and_saveexec_b64 s[56:57], s[54:55]
	s_cbranch_execz .LBB0_756
	v_lshl_or_b32 v180, v180, 6, v173
	v_cmp_le_i32_e32 vcc, v180, v160
	v_cmp_gt_i32_e64 s[0:1], v180, v171
	s_and_b64 s[10:11], vcc, s[0:1]
	v_cmp_lt_i32_e32 vcc, v180, v160
	v_cmp_ge_i32_e64 s[0:1], v180, v171
	v_or_b32_e32 v144, 2, v180
	s_and_b64 s[14:15], vcc, s[0:1]
	v_cmp_le_i32_e32 vcc, v144, v160
	v_cmp_gt_i32_e64 s[0:1], v144, v171
	v_or_b32_e32 v144, 3, v180
	s_and_b64 s[18:19], vcc, s[0:1]
	v_cmp_le_i32_e32 vcc, v144, v160
	v_cmp_gt_i32_e64 s[0:1], v144, v171
	v_or_b32_e32 v144, 4, v180
	s_and_b64 s[46:47], vcc, s[0:1]
	v_cmp_le_i32_e32 vcc, v144, v160
	v_cmp_gt_i32_e64 s[0:1], v144, v171
	v_or_b32_e32 v144, 5, v180
	ds_read_b128 v[132:135], v177
	ds_read_b128 v[136:139], v177 offset:64
	ds_read_b128 v[140:143], v177 offset:576
	ds_read_b128 v[128:131], v177 offset:640
	ds_read_b128 v[124:127], v178
	ds_read_b128 v[120:123], v178 offset:1280
	ds_read_b128 v[116:119], v178 offset:2560
	ds_read_b128 v[112:115], v178 offset:3840
	s_and_b64 s[12:13], vcc, s[0:1]
	v_cmp_le_i32_e32 vcc, v144, v160
	v_cmp_gt_i32_e64 s[0:1], v144, v171
	v_or_b32_e32 v148, 6, v180
	s_and_b64 s[16:17], vcc, s[0:1]
	v_cmp_le_i32_e32 vcc, v148, v160
	v_cmp_gt_i32_e64 s[0:1], v148, v171
	v_or_b32_e32 v180, 7, v180
	s_and_b64 s[48:49], vcc, s[0:1]
	v_cmp_le_i32_e32 vcc, v180, v160
	v_cmp_gt_i32_e64 s[0:1], v180, v171
	s_and_b64 s[50:51], vcc, s[0:1]
	s_and_b64 vcc, exec, s[8:9]
	v_mov_b32_e32 v226, 0xff800000
	v_cndmask_b32_e64 v218, v226, 0, s[10:11]
	v_cndmask_b32_e64 v219, v226, 0, s[14:15]
	v_cndmask_b32_e64 v220, v226, 0, s[18:19]
	v_cndmask_b32_e64 v221, v226, 0, s[46:47]
	v_cndmask_b32_e64 v222, v226, 0, s[12:13]
	v_cndmask_b32_e64 v223, v226, 0, s[16:17]
	v_cndmask_b32_e64 v224, v226, 0, s[48:49]
	v_cndmask_b32_e64 v225, v226, 0, s[50:51]
	s_nop 1
	s_waitcnt lgkmcnt(7)
	v_mfma_f32_16x16x32_bf16 v[144:147], v[132:135], v[8:11], v[218:221]
	s_waitcnt lgkmcnt(6)
	v_mfma_f32_16x16x32_bf16 v[148:151], v[136:139], v[12:15], v[144:147]
	s_waitcnt lgkmcnt(5)
	v_mfma_f32_16x16x32_bf16 v[144:147], v[140:143], v[8:11], v[222:225]
	s_waitcnt lgkmcnt(4)
	v_mfma_f32_16x16x32_bf16 v[144:147], v[128:131], v[12:15], v[144:147]
	s_nop 7
	s_cbranch_vccnz .LBB0_770
	v_mul_f32_e32 v180, 0x3e38aa3b, v148
	v_max_f32_e32 v180, 0xf149f2ca, v180
	v_cndmask_b32_e64 v180, v232, v180, s[10:11]
	v_mul_f32_e32 v181, 0x3e38aa3b, v149
	v_max_f32_e32 v181, v180, v181
	v_cndmask_b32_e64 v180, v180, v181, s[14:15]
	v_mul_f32_e32 v181, 0x3e38aa3b, v150
	v_max_f32_e32 v181, v180, v181
	v_cndmask_b32_e64 v180, v180, v181, s[18:19]
	v_mul_f32_e32 v181, 0x3e38aa3b, v151
	v_max_f32_e32 v181, v180, v181
	v_cndmask_b32_e64 v180, v180, v181, s[46:47]
	v_mul_f32_e32 v181, 0x3e38aa3b, v144
	v_max_f32_e32 v181, v180, v181
	v_cndmask_b32_e64 v180, v180, v181, s[12:13]
	v_mul_f32_e32 v181, 0x3e38aa3b, v145
	v_max_f32_e32 v182, v180, v180
	v_max_f32_e32 v181, v182, v181
	v_cndmask_b32_e64 v180, v180, v181, s[16:17]
	v_mul_f32_e32 v181, 0x3e38aa3b, v146
	v_max_f32_e32 v182, v180, v180
	v_max_f32_e32 v181, v182, v181
	v_cndmask_b32_e64 v180, v180, v181, s[48:49]
	v_mul_f32_e32 v181, 0x3e38aa3b, v147
	v_max_f32_e32 v182, v180, v180
	v_max_f32_e32 v181, v182, v181
	v_cndmask_b32_e64 v180, v180, v181, s[50:51]
	ds_bpermute_b32 v181, v175, v180
	v_max_f32_e32 v180, v180, v180
	s_waitcnt lgkmcnt(0)
	v_max_f32_e32 v181, v181, v181
	v_max_f32_e32 v180, v180, v181
	ds_bpermute_b32 v181, v159, v180
	s_waitcnt lgkmcnt(0)
	v_max3_f32 v181, v3, v180, v181
	v_sub_f32_e32 v3, v3, v181
	v_exp_f32_e32 v180, v3
	v_mov_b32_e32 v3, v181
	v_mul_f32_e32 v155, v155, v180
	v_pk_mul_f32 v[102:103], v[102:103], v[180:181] op_sel_hi:[1,0]
	v_pk_mul_f32 v[100:101], v[100:101], v[180:181] op_sel_hi:[1,0]
	v_pk_mul_f32 v[98:99], v[98:99], v[180:181] op_sel_hi:[1,0]
	v_pk_mul_f32 v[96:97], v[96:97], v[180:181] op_sel_hi:[1,0]
	v_pk_mul_f32 v[94:95], v[94:95], v[180:181] op_sel_hi:[1,0]
	v_pk_mul_f32 v[92:93], v[92:93], v[180:181] op_sel_hi:[1,0]
	v_pk_mul_f32 v[90:91], v[90:91], v[180:181] op_sel_hi:[1,0]
	v_pk_mul_f32 v[88:89], v[88:89], v[180:181] op_sel_hi:[1,0]
; #define MFMA16(a, b, c) __builtin_amdgcn_mfma_f32_16x16x32_bf16((a), (b), (c), 0, 0, 0)
; DI unsigned pk2(float lo, float hi) { f32x2 v = {lo, hi}; bf16x2_t b = __builtin_convertvector(v, bf16x2_t); return __builtin_bit_cast(unsigned, b); }
; template <int MODE>
; DI void nsa_chunk(const KVFrag& f, int kb, int t, bool selbit, const bf16x8 (&qf)[4][2], f32x4 (&O)[4][4], float (&m)[4], float (&l)[4], int quad, bool online) {
;     ...
;   for (int hh = 0; hh < 4; ++hh) {
;     f32x4 s[2];
; #pragma unroll
;     for (int a = 0; a < 2; ++a) { s[a] = MFMA16(f.k[a][0], qf[hh][0], ((f32x4){0.f, 0.f, 0.f, 0.f})); s[a] = MFMA16(f.k[a][1], qf[hh][1], s[a]); }
;     float mn = m[hh];
;     if (online) {
;       float cm = -1e30f;
; #pragma unroll
;       for (int idx = 0; idx < 8; ++idx) if (val[idx]) cm = fmaxf(cm, s[idx >> 2][idx & 3] * SC);
;       cm = fmaxf(cm, __shfl_xor(cm, 16)); cm = fmaxf(cm, __shfl_xor(cm, 32));
;       mn = fmaxf(mn, cm);
;       const float alpha = __builtin_amdgcn_exp2f(m[hh] - mn);
;       m[hh] = mn; l[hh] *= alpha;
; #pragma unroll
;       for (int dt = 0; dt < 4; ++dt) O[hh][dt] = O[hh][dt] * alpha;
;     }
;     float pv[8]; float ps = 0.f;
; #pragma unroll
;     for (int idx = 0; idx < 8; ++idx) { pv[idx] = val[idx] ? __builtin_amdgcn_exp2f(fmaf(s[idx >> 2][idx & 3], SC, -mn)) : 0.f; ps += pv[idx]; }
;     l[hh] += ps;
;     const bf16x8 pf = mk8((u32x4){pk2(pv[0], pv[1]), pk2(pv[2], pv[3]), pk2(pv[4], pv[5]), pk2(pv[6], pv[7])});
; #pragma unroll
;     for (int dt = 0; dt < 4; ++dt) O[hh][dt] = MFMA16(f.v[dt], pf, O[hh][dt]);
.LBB0_770:
	v_pk_fma_f32 v[148:149], v[148:149], s[34:35], v[2:3] op_sel:[0,0,1] op_sel_hi:[1,0,1] neg_lo:[0,0,1] neg_hi:[0,0,1]
	v_pk_fma_f32 v[150:151], v[150:151], s[34:35], v[2:3] op_sel:[0,0,1] op_sel_hi:[1,0,1] neg_lo:[0,0,1] neg_hi:[0,0,1]
	s_nop 2
	v_pk_fma_f32 v[144:145], v[144:145], s[34:35], v[2:3] op_sel:[0,0,1] op_sel_hi:[1,0,1] neg_lo:[0,0,1] neg_hi:[0,0,1]
	v_pk_fma_f32 v[146:147], v[146:147], s[34:35], v[2:3] op_sel:[0,0,1] op_sel_hi:[1,0,1] neg_lo:[0,0,1] neg_hi:[0,0,1]
	v_exp_f32_e32 v180, v148
	v_exp_f32_e32 v181, v149
	v_exp_f32_e32 v182, v150
	v_exp_f32_e32 v183, v151
	v_exp_f32_e32 v184, v144
	v_exp_f32_e32 v185, v145
	v_exp_f32_e32 v186, v146
	v_exp_f32_e32 v187, v147
	v_cvt_pk_bf16_f32 v144, v180, v181
	v_cvt_pk_bf16_f32 v145, v182, v183
	v_cvt_pk_bf16_f32 v146, v184, v185
	v_cvt_pk_bf16_f32 v147, v186, v187
	s_and_b64 vcc, exec, s[8:9]
	s_waitcnt lgkmcnt(3)
	v_mfma_f32_16x16x32_bf16 v[100:103], v[124:127], v[144:147], v[100:103]
	s_waitcnt lgkmcnt(2)
	v_mfma_f32_16x16x32_bf16 v[96:99], v[120:123], v[144:147], v[96:99]
	s_waitcnt lgkmcnt(1)
	v_mfma_f32_16x16x32_bf16 v[92:95], v[116:119], v[144:147], v[92:95]
	s_waitcnt lgkmcnt(0)
	v_mfma_f32_16x16x32_bf16 v[88:91], v[112:115], v[144:147], v[88:91]
	v_mfma_f32_16x16x32_bf16 v[144:147], v[132:135], v[16:19], v[218:221]
	v_mfma_f32_16x16x32_bf16 v[148:151], v[136:139], v[20:23], v[144:147]
	v_mfma_f32_16x16x32_bf16 v[144:147], v[140:143], v[16:19], v[222:225]
	v_mfma_f32_16x16x32_bf16 v[144:147], v[128:131], v[20:23], v[144:147]
	s_cbranch_vccnz .LBB0_772
	s_nop 4
	v_mul_f32_e32 v188, 0x3e38aa3b, v148
	v_max_f32_e32 v188, 0xf149f2ca, v188
	v_cndmask_b32_e64 v188, v232, v188, s[10:11]
	v_mul_f32_e32 v189, 0x3e38aa3b, v149
	v_max_f32_e32 v189, v188, v189
	v_cndmask_b32_e64 v188, v188, v189, s[14:15]
	v_mul_f32_e32 v189, 0x3e38aa3b, v150
	v_max_f32_e32 v189, v188, v189
	v_cndmask_b32_e64 v188, v188, v189, s[18:19]
	v_mul_f32_e32 v189, 0x3e38aa3b, v151
	v_max_f32_e32 v189, v188, v189
	v_cndmask_b32_e64 v188, v188, v189, s[46:47]
	v_mul_f32_e32 v189, 0x3e38aa3b, v144
	v_max_f32_e32 v189, v188, v189
	v_cndmask_b32_e64 v188, v188, v189, s[12:13]
	v_mul_f32_e32 v189, 0x3e38aa3b, v145
	v_max_f32_e32 v190, v188, v188
	v_max_f32_e32 v189, v190, v189
	v_cndmask_b32_e64 v188, v188, v189, s[16:17]
	v_mul_f32_e32 v189, 0x3e38aa3b, v146
	v_max_f32_e32 v190, v188, v188
	v_max_f32_e32 v189, v190, v189
	v_cndmask_b32_e64 v188, v188, v189, s[48:49]
	v_mul_f32_e32 v189, 0x3e38aa3b, v147
	v_max_f32_e32 v190, v188, v188
	v_max_f32_e32 v189, v190, v189
	v_cndmask_b32_e64 v188, v188, v189, s[50:51]
	ds_bpermute_b32 v189, v175, v188
	v_max_f32_e32 v188, v188, v188
	s_waitcnt lgkmcnt(0)
	v_max_f32_e32 v189, v189, v189
	v_max_f32_e32 v188, v188, v189
	ds_bpermute_b32 v189, v159, v188
	s_waitcnt lgkmcnt(0)
	v_max3_f32 v188, v2, v188, v189
	v_sub_f32_e32 v2, v2, v188
	v_exp_f32_e32 v2, v2
	s_nop 0
	v_mul_f32_e32 v154, v154, v2
	v_pk_mul_f32 v[86:87], v[86:87], v[2:3] op_sel_hi:[1,0]
	v_pk_mul_f32 v[84:85], v[84:85], v[2:3] op_sel_hi:[1,0]
	v_pk_mul_f32 v[82:83], v[82:83], v[2:3] op_sel_hi:[1,0]
	v_pk_mul_f32 v[80:81], v[80:81], v[2:3] op_sel_hi:[1,0]
	v_pk_mul_f32 v[78:79], v[78:79], v[2:3] op_sel_hi:[1,0]
	v_pk_mul_f32 v[76:77], v[76:77], v[2:3] op_sel_hi:[1,0]
	v_pk_mul_f32 v[74:75], v[74:75], v[2:3] op_sel_hi:[1,0]
	v_pk_mul_f32 v[72:73], v[72:73], v[2:3] op_sel_hi:[1,0]
	v_mov_b32_e32 v2, v188
; #define MFMA16(a, b, c) __builtin_amdgcn_mfma_f32_16x16x32_bf16((a), (b), (c), 0, 0, 0)
; DI unsigned pk2(float lo, float hi) { f32x2 v = {lo, hi}; bf16x2_t b = __builtin_convertvector(v, bf16x2_t); return __builtin_bit_cast(unsigned, b); }
; template <int MODE>
; DI void nsa_chunk(const KVFrag& f, int kb, int t, bool selbit, const bf16x8 (&qf)[4][2], f32x4 (&O)[4][4], float (&m)[4], float (&l)[4], int quad, bool online) {
;     ...
;   for (int hh = 0; hh < 4; ++hh) {
;     f32x4 s[2];
; #pragma unroll
;     for (int a = 0; a < 2; ++a) { s[a] = MFMA16(f.k[a][0], qf[hh][0], ((f32x4){0.f, 0.f, 0.f, 0.f})); s[a] = MFMA16(f.k[a][1], qf[hh][1], s[a]); }
;     float mn = m[hh];
;     if (online) {
;       float cm = -1e30f;
; #pragma unroll
;       for (int idx = 0; idx < 8; ++idx) if (val[idx]) cm = fmaxf(cm, s[idx >> 2][idx & 3] * SC);
;       cm = fmaxf(cm, __shfl_xor(cm, 16)); cm = fmaxf(cm, __shfl_xor(cm, 32));
;       mn = fmaxf(mn, cm);
;       const float alpha = __builtin_amdgcn_exp2f(m[hh] - mn);
;       m[hh] = mn; l[hh] *= alpha;
; #pragma unroll
;       for (int dt = 0; dt < 4; ++dt) O[hh][dt] = O[hh][dt] * alpha;
;     }
;     float pv[8]; float ps = 0.f;
; #pragma unroll
;     for (int idx = 0; idx < 8; ++idx) { pv[idx] = val[idx] ? __builtin_amdgcn_exp2f(fmaf(s[idx >> 2][idx & 3], SC, -mn)) : 0.f; ps += pv[idx]; }
;     l[hh] += ps;
;     const bf16x8 pf = mk8((u32x4){pk2(pv[0], pv[1]), pk2(pv[2], pv[3]), pk2(pv[4], pv[5]), pk2(pv[6], pv[7])});
; #pragma unroll
;     for (int dt = 0; dt < 4; ++dt) O[hh][dt] = MFMA16(f.v[dt], pf, O[hh][dt]);
.LBB0_772:
	s_nop 4
	v_pk_fma_f32 v[148:149], v[148:149], s[34:35], v[2:3] op_sel_hi:[1,0,0] neg_lo:[0,0,1] neg_hi:[0,0,1]
	v_pk_fma_f32 v[150:151], v[150:151], s[34:35], v[2:3] op_sel_hi:[1,0,0] neg_lo:[0,0,1] neg_hi:[0,0,1]
	v_pk_fma_f32 v[144:145], v[144:145], s[34:35], v[2:3] op_sel_hi:[1,0,0] neg_lo:[0,0,1] neg_hi:[0,0,1]
	v_pk_fma_f32 v[146:147], v[146:147], s[34:35], v[2:3] op_sel_hi:[1,0,0] neg_lo:[0,0,1] neg_hi:[0,0,1]
	v_exp_f32_e32 v188, v148
	v_exp_f32_e32 v189, v149
	v_exp_f32_e32 v190, v150
	v_exp_f32_e32 v191, v151
	v_exp_f32_e32 v192, v144
	v_exp_f32_e32 v193, v145
	v_exp_f32_e32 v194, v146
	v_exp_f32_e32 v195, v147
	v_cvt_pk_bf16_f32 v144, v188, v189
	v_cvt_pk_bf16_f32 v145, v190, v191
	v_cvt_pk_bf16_f32 v146, v192, v193
	v_cvt_pk_bf16_f32 v147, v194, v195
	s_and_b64 vcc, exec, s[8:9]
	s_nop 0
	v_mfma_f32_16x16x32_bf16 v[84:87], v[124:127], v[144:147], v[84:87]
	v_mfma_f32_16x16x32_bf16 v[80:83], v[120:123], v[144:147], v[80:83]
	v_mfma_f32_16x16x32_bf16 v[76:79], v[116:119], v[144:147], v[76:79]
	v_mfma_f32_16x16x32_bf16 v[72:75], v[112:115], v[144:147], v[72:75]
	v_mfma_f32_16x16x32_bf16 v[144:147], v[132:135], v[24:27], v[218:221]
	v_mfma_f32_16x16x32_bf16 v[148:151], v[136:139], v[28:31], v[144:147]
	v_mfma_f32_16x16x32_bf16 v[144:147], v[140:143], v[24:27], v[222:225]
	v_mfma_f32_16x16x32_bf16 v[144:147], v[128:131], v[28:31], v[144:147]
	s_cbranch_vccnz .LBB0_774
	s_nop 4
	v_mul_f32_e32 v196, 0x3e38aa3b, v148
	v_max_f32_e32 v196, 0xf149f2ca, v196
	v_cndmask_b32_e64 v196, v232, v196, s[10:11]
	v_mul_f32_e32 v197, 0x3e38aa3b, v149
	v_max_f32_e32 v197, v196, v197
	v_cndmask_b32_e64 v196, v196, v197, s[14:15]
	v_mul_f32_e32 v197, 0x3e38aa3b, v150
	v_max_f32_e32 v197, v196, v197
	v_cndmask_b32_e64 v196, v196, v197, s[18:19]
	v_mul_f32_e32 v197, 0x3e38aa3b, v151
	v_max_f32_e32 v197, v196, v197
	v_cndmask_b32_e64 v196, v196, v197, s[46:47]
	v_mul_f32_e32 v197, 0x3e38aa3b, v144
	v_max_f32_e32 v197, v196, v197
	v_cndmask_b32_e64 v196, v196, v197, s[12:13]
	v_mul_f32_e32 v197, 0x3e38aa3b, v145
	v_max_f32_e32 v198, v196, v196
	v_max_f32_e32 v197, v198, v197
	v_cndmask_b32_e64 v196, v196, v197, s[16:17]
	v_mul_f32_e32 v197, 0x3e38aa3b, v146
	v_max_f32_e32 v198, v196, v196
	v_max_f32_e32 v197, v198, v197
	v_cndmask_b32_e64 v196, v196, v197, s[48:49]
	v_mul_f32_e32 v197, 0x3e38aa3b, v147
	v_max_f32_e32 v198, v196, v196
	v_max_f32_e32 v197, v198, v197
	v_cndmask_b32_e64 v196, v196, v197, s[50:51]
	ds_bpermute_b32 v197, v175, v196
	v_max_f32_e32 v196, v196, v196
	s_waitcnt lgkmcnt(0)
	v_max_f32_e32 v197, v197, v197
	v_max_f32_e32 v196, v196, v197
	ds_bpermute_b32 v197, v159, v196
	s_waitcnt lgkmcnt(0)
	v_max3_f32 v196, v0, v196, v197
	v_sub_f32_e32 v0, v0, v196
	v_exp_f32_e32 v0, v0
	s_nop 0
	v_mul_f32_e32 v153, v153, v0
	v_pk_mul_f32 v[70:71], v[70:71], v[0:1] op_sel_hi:[1,0]
	v_pk_mul_f32 v[68:69], v[68:69], v[0:1] op_sel_hi:[1,0]
	v_pk_mul_f32 v[66:67], v[66:67], v[0:1] op_sel_hi:[1,0]
	v_pk_mul_f32 v[64:65], v[64:65], v[0:1] op_sel_hi:[1,0]
	v_pk_mul_f32 v[62:63], v[62:63], v[0:1] op_sel_hi:[1,0]
	v_pk_mul_f32 v[60:61], v[60:61], v[0:1] op_sel_hi:[1,0]
	v_pk_mul_f32 v[58:59], v[58:59], v[0:1] op_sel_hi:[1,0]
	v_pk_mul_f32 v[56:57], v[56:57], v[0:1] op_sel_hi:[1,0]
	v_mov_b32_e32 v0, v196
.LBB0_774:
	v_mfma_f32_16x16x32_bf16 v[132:135], v[132:135], v[32:35], v[218:221]
	s_nop 3
	v_pk_fma_f32 v[148:149], v[148:149], s[34:35], v[0:1] op_sel_hi:[1,0,0] neg_lo:[0,0,1] neg_hi:[0,0,1]
	v_pk_fma_f32 v[150:151], v[150:151], s[34:35], v[0:1] op_sel_hi:[1,0,0] neg_lo:[0,0,1] neg_hi:[0,0,1]
	v_pk_fma_f32 v[144:145], v[144:145], s[34:35], v[0:1] op_sel_hi:[1,0,0] neg_lo:[0,0,1] neg_hi:[0,0,1]
	v_pk_fma_f32 v[146:147], v[146:147], s[34:35], v[0:1] op_sel_hi:[1,0,0] neg_lo:[0,0,1] neg_hi:[0,0,1]
	v_mfma_f32_16x16x32_bf16 v[132:135], v[136:139], v[36:39], v[132:135]
	v_exp_f32_e32 v148, v148
	v_exp_f32_e32 v149, v149
	v_exp_f32_e32 v150, v150
	v_mfma_f32_16x16x32_bf16 v[136:139], v[140:143], v[32:35], v[222:225]
	v_exp_f32_e32 v151, v151
	v_exp_f32_e32 v144, v144
	v_exp_f32_e32 v145, v145
	v_exp_f32_e32 v146, v146
	v_exp_f32_e32 v147, v147
	v_cvt_pk_bf16_f32 v196, v148, v149
	v_cvt_pk_bf16_f32 v197, v150, v151
	v_cvt_pk_bf16_f32 v198, v144, v145
	v_cvt_pk_bf16_f32 v199, v146, v147
	v_mfma_f32_16x16x32_bf16 v[128:131], v[128:131], v[36:39], v[136:139]
	s_and_b64 vcc, exec, s[8:9]
	v_mfma_f32_16x16x32_bf16 v[68:71], v[124:127], v[196:199], v[68:71]
	v_mfma_f32_16x16x32_bf16 v[64:67], v[120:123], v[196:199], v[64:67]
	v_mfma_f32_16x16x32_bf16 v[60:63], v[116:119], v[196:199], v[60:63]
	v_mfma_f32_16x16x32_bf16 v[56:59], v[112:115], v[196:199], v[56:59]
	s_cbranch_vccnz .LBB0_755
	v_mul_f32_e32 v136, 0x3e38aa3b, v132
	v_max_f32_e32 v136, 0xf149f2ca, v136
	v_cndmask_b32_e64 v136, v232, v136, s[10:11]
	v_mul_f32_e32 v137, 0x3e38aa3b, v133
	v_max_f32_e32 v137, v136, v137
	v_cndmask_b32_e64 v136, v136, v137, s[14:15]
	v_mul_f32_e32 v137, 0x3e38aa3b, v134
	v_max_f32_e32 v137, v136, v137
	v_cndmask_b32_e64 v136, v136, v137, s[18:19]
	v_mul_f32_e32 v137, 0x3e38aa3b, v135
	v_max_f32_e32 v137, v136, v137
	v_cndmask_b32_e64 v136, v136, v137, s[46:47]
	v_mul_f32_e32 v137, 0x3e38aa3b, v128
	v_max_f32_e32 v137, v136, v137
	v_cndmask_b32_e64 v136, v136, v137, s[12:13]
	v_mul_f32_e32 v137, 0x3e38aa3b, v129
	v_max_f32_e32 v138, v136, v136
	v_max_f32_e32 v137, v138, v137
	v_cndmask_b32_e64 v136, v136, v137, s[16:17]
	v_mul_f32_e32 v137, 0x3e38aa3b, v130
	v_max_f32_e32 v138, v136, v136
	v_max_f32_e32 v137, v138, v137
	v_cndmask_b32_e64 v136, v136, v137, s[48:49]
	v_mul_f32_e32 v137, 0x3e38aa3b, v131
	v_max_f32_e32 v138, v136, v136
	v_max_f32_e32 v137, v138, v137
	v_cndmask_b32_e64 v136, v136, v137, s[50:51]
	ds_bpermute_b32 v137, v175, v136
	v_max_f32_e32 v136, v136, v136
	s_waitcnt lgkmcnt(0)
	v_max_f32_e32 v137, v137, v137
	v_max_f32_e32 v136, v136, v137
	ds_bpermute_b32 v137, v159, v136
	s_waitcnt lgkmcnt(0)
	v_max3_f32 v137, v179, v136, v137
	v_sub_f32_e32 v136, v179, v137
	v_exp_f32_e32 v136, v136
	v_mov_b32_e32 v179, v137
	v_mul_f32_e32 v152, v152, v136
	v_pk_mul_f32 v[54:55], v[54:55], v[136:137] op_sel_hi:[1,0]
	v_pk_mul_f32 v[52:53], v[52:53], v[136:137] op_sel_hi:[1,0]
	v_pk_mul_f32 v[50:51], v[50:51], v[136:137] op_sel_hi:[1,0]
	v_pk_mul_f32 v[48:49], v[48:49], v[136:137] op_sel_hi:[1,0]
	v_pk_mul_f32 v[46:47], v[46:47], v[136:137] op_sel_hi:[1,0]
	v_pk_mul_f32 v[44:45], v[44:45], v[136:137] op_sel_hi:[1,0]
	v_pk_mul_f32 v[42:43], v[42:43], v[136:137] op_sel_hi:[1,0]
	v_pk_mul_f32 v[40:41], v[40:41], v[136:137] op_sel_hi:[1,0]
	s_branch .LBB0_755
